# gl1 item loop: end-of-item LDS-reuse barrier moved to just before the next item's first LDS write (next item's global loads issue before the wait)
# baseline (speedup 1.0000x reference)
; __device__ __forceinline__ void gl1_item(PREF p, int l, int item, bool valid, LAS unsigned char* pl, int sw, int lane) {
;     ...
;     __syncthreads();
;     ...
;     __syncthreads();
.Lgl1_skip:
	s_barrier
	s_branch .LBB0_199

; __device__ __forceinline__ void gl1_item(PREF p, int l, int item, bool valid, LAS unsigned char* pl, int sw, int lane) {
;     ...
;     __syncthreads();
; __global__ void __launch_bounds__(NTHREADS, 2) mega_fwd(Params p_arg) {
;     ...
;             for (int it = 0; it * NP < 2 * NCH * 4; ++it) { const int item = it * NP + pgid; gl1_item(p, l, item, item < 2 * NCH * 4, lds + (wave >> 1) * 37376, wave & 1, lane); }
.LBB0_183:
	s_add_i32 s40, s40, 1
	s_mul_i32 s0, s40, s85
	s_cmpk_gt_i32 s0, 0x81f
	s_mov_b32 s33, 0x9000
	s_cbranch_scc1 .Lgl1_exit

; __device__ __forceinline__ unsigned pk2(float lo, float hi) { unsigned r; asm("v_cvt_pk_bf16_f32 %0, %1, %2" : "=v"(r) : "v"(lo), "v"(hi)); return r; }
; __device__ __forceinline__ void gl1_item(PREF p, int l, int item, bool valid, LAS unsigned char* pl, int sw, int lane) {
;     ...
;         unsigned wupp[8];
; #pragma unroll
;         for (int r2 = 0; r2 < 8; ++r2) wupp[r2] = pk2(p.gla_wup[(size_t)((l * 2 + d) * 16 + 2 * r2) * 256 + h * 64 + lane], p.gla_wup[(size_t)((l * 2 + d) * 16 + 2 * r2 + 1) * 256 + h * 64 + lane]);
;         const float bup = p.gla_bup[(l * 2 + d) * 256 + h * 64 + lane];
; #pragma unroll 1
;         for (int g2 = 0; g2 < 2; ++g2) {
;             unsigned vr[16];
; #pragma unroll
;             for (int ii = 0; ii < 16; ++ii) { const int i = 32 * sw + g2 * 16 + ii; vr[ii] = *(const unsigned*)(P + (size_t)(row0 + i * rstride) * PW + 1536 + h * 128 + 2 * lane); }
; #pragma unroll
;             for (int ii = 0; ii < 16; ++ii) { const int i = 32 * sw + g2 * 16 + ii; sVt[(2 * lane) * 72 + i] = (bf16_t)(vr[ii] & 0xffffu); sVt[(2 * lane + 1) * 72 + i] = (bf16_t)(vr[ii] >> 16); }
;         }
;         float bc = 0.f;
; #pragma unroll 1
;         for (int g4 = 0; g4 < 4; ++g4) {
;             float qn[16], kn[16];
;             if (g4 < 3) {
; #pragma unroll
;                 for (int ss = 0; ss < 16; ++ss) { const int s = (g4 + 1) * 16 + ss; const int i = d ? 63 - s : s; const bf16_t* pr = P + (size_t)(row0 + i * rstride) * PW + h * 64 + lane;
;                     qn[ss] = __builtin_bit_cast(float, (unsigned)pr[1024]); kn[ss] = __builtin_bit_cast(float, (unsigned)pr[1280]); }
;                 __builtin_amdgcn_sched_barrier(0);
;             }
.Lgl1v_fwd:
	s_mul_i32 s45, s46, 0x2400
	s_add_i32 s45, s45, s47
	s_add_i32 s45, s45, 0x4800
	s_lshl_b32 s50, s30, 1
	s_add_i32 s45, s45, s50
	s_movk_i32 s50, 0x90
	v_mul_u32_u24_e32 v60, 0x90, v64
	v_add_u32_e32 v60, s45, v60
	s_lshl_b32 s50, s2, 1
	v_mov_b32_e32 v61, s50
	s_waitcnt vmcnt(32)
	v_cvt_pk_bf16_f32 v8, v90, v91
	v_cvt_pk_bf16_f32 v9, v92, v93
	v_cvt_pk_bf16_f32 v10, v94, v95
	v_cvt_pk_bf16_f32 v11, v96, v97
	v_cvt_pk_bf16_f32 v12, v98, v99
	v_cvt_pk_bf16_f32 v13, v100, v101
	v_cvt_pk_bf16_f32 v14, v102, v103
	v_cvt_pk_bf16_f32 v15, v104, v105
	s_waitcnt vmcnt(0)
	v_mul_u32_u24_e32 v86, 0x120, v64
	s_lshl_b32 s45, s46, 6
	s_add_i32 s45, s45, s47
	v_add_u32_e32 v86, s45, v86
	s_barrier
	ds_write_b16 v86, v34 offset:0
	ds_write_b16_d16_hi v86, v34 offset:144
	ds_write_b16 v86, v35 offset:2
	ds_write_b16_d16_hi v86, v35 offset:146
	ds_write_b16 v86, v36 offset:4
	ds_write_b16_d16_hi v86, v36 offset:148
	ds_write_b16 v86, v37 offset:6
	ds_write_b16_d16_hi v86, v37 offset:150
	ds_write_b16 v86, v38 offset:8
	ds_write_b16_d16_hi v86, v38 offset:152
	ds_write_b16 v86, v39 offset:10
	ds_write_b16_d16_hi v86, v39 offset:154
	ds_write_b16 v86, v40 offset:12
	ds_write_b16_d16_hi v86, v40 offset:156
	ds_write_b16 v86, v41 offset:14
	ds_write_b16_d16_hi v86, v41 offset:158
	ds_write_b16 v86, v42 offset:16
	ds_write_b16_d16_hi v86, v42 offset:160
	ds_write_b16 v86, v43 offset:18
	ds_write_b16_d16_hi v86, v43 offset:162
	ds_write_b16 v86, v44 offset:20
	ds_write_b16_d16_hi v86, v44 offset:164
	ds_write_b16 v86, v45 offset:22
	ds_write_b16_d16_hi v86, v45 offset:166
	ds_write_b16 v86, v46 offset:24
	ds_write_b16_d16_hi v86, v46 offset:168
	ds_write_b16 v86, v47 offset:26
	ds_write_b16_d16_hi v86, v47 offset:170
	ds_write_b16 v86, v212 offset:28
	ds_write_b16_d16_hi v86, v212 offset:172
	ds_write_b16 v86, v213 offset:30
	ds_write_b16_d16_hi v86, v213 offset:174
	ds_write_b16 v86, v214 offset:32
	ds_write_b16_d16_hi v86, v214 offset:176
	ds_write_b16 v86, v215 offset:34
	ds_write_b16_d16_hi v86, v215 offset:178
	ds_write_b16 v86, v216 offset:36
	ds_write_b16_d16_hi v86, v216 offset:180
	ds_write_b16 v86, v217 offset:38
	ds_write_b16_d16_hi v86, v217 offset:182
	ds_write_b16 v86, v218 offset:40
	ds_write_b16_d16_hi v86, v218 offset:184
	ds_write_b16 v86, v219 offset:42
	ds_write_b16_d16_hi v86, v219 offset:186
	ds_write_b16 v86, v222 offset:44
	ds_write_b16_d16_hi v86, v222 offset:188
	ds_write_b16 v86, v223 offset:46
	ds_write_b16_d16_hi v86, v223 offset:190
	ds_write_b16 v86, v228 offset:48
	ds_write_b16_d16_hi v86, v228 offset:192
	ds_write_b16 v86, v229 offset:50
	ds_write_b16_d16_hi v86, v229 offset:194
	ds_write_b16 v86, v230 offset:52
	ds_write_b16_d16_hi v86, v230 offset:196
	ds_write_b16 v86, v231 offset:54
	ds_write_b16_d16_hi v86, v231 offset:198
	ds_write_b16 v86, v232 offset:56
	ds_write_b16_d16_hi v86, v232 offset:200
	ds_write_b16 v86, v233 offset:58
	ds_write_b16_d16_hi v86, v233 offset:202
	ds_write_b16 v86, v234 offset:60
	ds_write_b16_d16_hi v86, v234 offset:204
	ds_write_b16 v86, v235 offset:62
	ds_write_b16_d16_hi v86, v235 offset:206
	global_load_ushort v148, v134, s[6:7]
	global_load_ushort v164, v134, s[6:7] offset:512
	s_add_u32 s6, s6, s54
	s_addc_u32 s7, s7, s55
	global_load_ushort v149, v134, s[6:7]
	global_load_ushort v165, v134, s[6:7] offset:512
	s_add_u32 s6, s6, s54
	s_addc_u32 s7, s7, s55
	global_load_ushort v150, v134, s[6:7]
	global_load_ushort v166, v134, s[6:7] offset:512
	s_add_u32 s6, s6, s54
	s_addc_u32 s7, s7, s55
	global_load_ushort v151, v134, s[6:7]
	global_load_ushort v167, v134, s[6:7] offset:512
	s_add_u32 s6, s6, s54
	s_addc_u32 s7, s7, s55
	global_load_ushort v152, v134, s[6:7]
	global_load_ushort v168, v134, s[6:7] offset:512
	s_add_u32 s6, s6, s54
	s_addc_u32 s7, s7, s55
	global_load_ushort v153, v134, s[6:7]
	global_load_ushort v169, v134, s[6:7] offset:512
	s_add_u32 s6, s6, s54
	s_addc_u32 s7, s7, s55
	global_load_ushort v154, v134, s[6:7]
	global_load_ushort v170, v134, s[6:7] offset:512
	s_add_u32 s6, s6, s54
	s_addc_u32 s7, s7, s55
	global_load_ushort v155, v134, s[6:7]
	global_load_ushort v171, v134, s[6:7] offset:512
	s_add_u32 s6, s6, s54
	s_addc_u32 s7, s7, s55
	global_load_ushort v156, v134, s[6:7]
	global_load_ushort v172, v134, s[6:7] offset:512
	s_add_u32 s6, s6, s54
	s_addc_u32 s7, s7, s55
	global_load_ushort v157, v134, s[6:7]
	global_load_ushort v173, v134, s[6:7] offset:512
	s_add_u32 s6, s6, s54
	s_addc_u32 s7, s7, s55
	global_load_ushort v158, v134, s[6:7]
	global_load_ushort v174, v134, s[6:7] offset:512
	s_add_u32 s6, s6, s54
	s_addc_u32 s7, s7, s55
	global_load_ushort v159, v134, s[6:7]
	global_load_ushort v175, v134, s[6:7] offset:512
	s_add_u32 s6, s6, s54
	s_addc_u32 s7, s7, s55
	global_load_ushort v160, v134, s[6:7]
	global_load_ushort v176, v134, s[6:7] offset:512
	s_add_u32 s6, s6, s54
	s_addc_u32 s7, s7, s55
	global_load_ushort v161, v134, s[6:7]
	global_load_ushort v177, v134, s[6:7] offset:512
	s_add_u32 s6, s6, s54
	s_addc_u32 s7, s7, s55
	global_load_ushort v162, v134, s[6:7]
	global_load_ushort v178, v134, s[6:7] offset:512
	s_add_u32 s6, s6, s54
	s_addc_u32 s7, s7, s55
	global_load_ushort v163, v134, s[6:7]
	global_load_ushort v179, v134, s[6:7] offset:512
	s_add_u32 s6, s6, s54
	s_addc_u32 s7, s7, s55
	v_mov_b32_e32 v17, 0
	s_mov_b32 s1, 0xbfb8aa3b
	s_mov_b32 s49, 0xbd800000
	v_mov_b32_e32 v236, v16
	v_mov_b32_e32 v106, v124
	v_mov_b32_e32 v237, v16
	v_mov_b32_e32 v107, v124
	v_mov_b32_e32 v238, v16
	v_mov_b32_e32 v108, v124
	v_mov_b32_e32 v239, v16
	v_mov_b32_e32 v109, v124
	v_mov_b32_e32 v240, v16
	v_mov_b32_e32 v110, v124
	v_mov_b32_e32 v241, v16
; __device__ __forceinline__ void gl1_item(PREF p, int l, int item, bool valid, LAS unsigned char* pl, int sw, int lane) {
;     ...
;             float gv[16];
; #pragma unroll
;             for (int ss = 0; ss < 16; ++ss) { const int s = g4 * 16 + ss; const int i = d ? 63 - s : s;
;                 float z = bup;
; #pragma unroll
;                 for (int r2 = 0; r2 < 8; ++r2) { const unsigned w = (unsigned)__builtin_amdgcn_readlane((int)lrp[r2], i);
;                     z = __builtin_amdgcn_fdot2_f32_bf16(__builtin_bit_cast(bf16x2_t, w), __builtin_bit_cast(bf16x2_t, wupp[r2]), z, false); }
;                 gv[ss] = -(fmaxf(-z, 0.f) + __logf(1.f + __expf(-fabsf(z)))) * (1.f / 16.f);
;                 __builtin_amdgcn_sched_barrier(0);
;             }
	v_mov_b32_e32 v111, v124
	v_mov_b32_e32 v242, v16
	v_mov_b32_e32 v112, v124
	v_mov_b32_e32 v243, v16
	v_mov_b32_e32 v113, v124
	v_mov_b32_e32 v244, v16
	v_mov_b32_e32 v114, v124
	v_mov_b32_e32 v245, v16
	v_mov_b32_e32 v115, v124
	v_mov_b32_e32 v246, v16
	v_mov_b32_e32 v116, v124
	v_mov_b32_e32 v247, v16
	v_mov_b32_e32 v117, v124
	v_mov_b32_e32 v248, v16
	v_mov_b32_e32 v118, v124
	v_mov_b32_e32 v249, v16
	v_mov_b32_e32 v119, v124
	v_mov_b32_e32 v250, v16
	v_mov_b32_e32 v120, v124
	v_mov_b32_e32 v251, v16
	v_mov_b32_e32 v121, v124
	s_nop 1
	v_mfma_f32_32x32x16_bf16 v[236:251], v[0:3], v[8:11], v[236:251]
	v_mfma_f32_32x32x16_bf16 v[106:121], v[0:3], v[12:15], v[106:121]
	s_nop 15
	s_nop 15
	v_permlane32_swap_b32 v236, v106
	v_permlane32_swap_b32 v237, v107
	v_permlane32_swap_b32 v238, v108
	v_permlane32_swap_b32 v239, v109
	v_permlane32_swap_b32 v240, v110
	v_permlane32_swap_b32 v241, v111
	v_permlane32_swap_b32 v242, v112
	v_permlane32_swap_b32 v243, v113
	v_permlane32_swap_b32 v244, v114
	v_permlane32_swap_b32 v245, v115
	v_permlane32_swap_b32 v246, v116
	v_permlane32_swap_b32 v247, v117
	v_permlane32_swap_b32 v248, v118
	v_permlane32_swap_b32 v249, v119
	v_permlane32_swap_b32 v250, v120
	v_permlane32_swap_b32 v251, v121
	v_mul_f32_e64 v18, |v236|, s1
	v_mul_f32_e64 v19, |v237|, s1
	v_mul_f32_e64 v20, |v238|, s1
	v_mul_f32_e64 v21, |v239|, s1
	v_mul_f32_e64 v22, |v106|, s1
	v_mul_f32_e64 v23, |v107|, s1
	v_mul_f32_e64 v24, |v108|, s1
	v_mul_f32_e64 v25, |v109|, s1
	v_mul_f32_e64 v26, |v240|, s1
	v_mul_f32_e64 v27, |v241|, s1
	v_mul_f32_e64 v28, |v242|, s1
	v_mul_f32_e64 v29, |v243|, s1
	v_mul_f32_e64 v30, |v110|, s1
	v_mul_f32_e64 v31, |v111|, s1
	v_mul_f32_e64 v32, |v112|, s1
	v_mul_f32_e64 v33, |v113|, s1
	v_exp_f32_e32 v18, v18
	v_exp_f32_e32 v19, v19
	v_exp_f32_e32 v20, v20
	v_exp_f32_e32 v21, v21
	v_exp_f32_e32 v22, v22
	v_exp_f32_e32 v23, v23
	v_exp_f32_e32 v24, v24
	v_exp_f32_e32 v25, v25
	v_exp_f32_e32 v26, v26
	v_exp_f32_e32 v27, v27
	v_exp_f32_e32 v28, v28
	v_exp_f32_e32 v29, v29
	v_exp_f32_e32 v30, v30
	v_exp_f32_e32 v31, v31
	v_exp_f32_e32 v32, v32
	v_exp_f32_e32 v33, v33
	v_max_f32_e64 v236, -v236, 0
	v_max_f32_e64 v237, -v237, 0
	v_max_f32_e64 v238, -v238, 0
	v_max_f32_e64 v239, -v239, 0
	v_max_f32_e64 v106, -v106, 0
	v_max_f32_e64 v107, -v107, 0
	v_max_f32_e64 v108, -v108, 0
	v_max_f32_e64 v109, -v109, 0
	v_max_f32_e64 v240, -v240, 0
	v_max_f32_e64 v241, -v241, 0
	v_max_f32_e64 v242, -v242, 0
	v_max_f32_e64 v243, -v243, 0
	v_max_f32_e64 v110, -v110, 0
	v_max_f32_e64 v111, -v111, 0
	v_max_f32_e64 v112, -v112, 0
	v_max_f32_e64 v113, -v113, 0
	v_add_f32_e32 v18, 1.0, v18
	v_add_f32_e32 v19, 1.0, v19
	v_add_f32_e32 v20, 1.0, v20
	v_add_f32_e32 v21, 1.0, v21
	v_add_f32_e32 v22, 1.0, v22
	v_add_f32_e32 v23, 1.0, v23
	v_add_f32_e32 v24, 1.0, v24
	v_add_f32_e32 v25, 1.0, v25
	v_add_f32_e32 v26, 1.0, v26
	v_add_f32_e32 v27, 1.0, v27
	v_add_f32_e32 v28, 1.0, v28
	v_add_f32_e32 v29, 1.0, v29
	v_add_f32_e32 v30, 1.0, v30
	v_add_f32_e32 v31, 1.0, v31
	v_add_f32_e32 v32, 1.0, v32
	v_add_f32_e32 v33, 1.0, v33
	v_log_f32_e32 v18, v18
	v_log_f32_e32 v19, v19
	v_log_f32_e32 v20, v20
	v_log_f32_e32 v21, v21
	v_log_f32_e32 v22, v22
	v_log_f32_e32 v23, v23
	v_log_f32_e32 v24, v24
	v_log_f32_e32 v25, v25
	v_log_f32_e32 v26, v26
	v_log_f32_e32 v27, v27
	v_log_f32_e32 v28, v28
	v_log_f32_e32 v29, v29
	v_log_f32_e32 v30, v30
	v_log_f32_e32 v31, v31
	v_log_f32_e32 v32, v32
	v_log_f32_e32 v33, v33
	v_fmac_f32_e32 v236, 0x3f317218, v18
	v_fmac_f32_e32 v237, 0x3f317218, v19
	v_fmac_f32_e32 v238, 0x3f317218, v20
	v_fmac_f32_e32 v239, 0x3f317218, v21
	v_fmac_f32_e32 v106, 0x3f317218, v22
	v_fmac_f32_e32 v107, 0x3f317218, v23
	v_fmac_f32_e32 v108, 0x3f317218, v24
	v_fmac_f32_e32 v109, 0x3f317218, v25
	v_fmac_f32_e32 v240, 0x3f317218, v26
	v_fmac_f32_e32 v241, 0x3f317218, v27
	v_fmac_f32_e32 v242, 0x3f317218, v28
	v_fmac_f32_e32 v243, 0x3f317218, v29
	v_fmac_f32_e32 v110, 0x3f317218, v30
	v_fmac_f32_e32 v111, 0x3f317218, v31
	v_fmac_f32_e32 v112, 0x3f317218, v32
	v_fmac_f32_e32 v113, 0x3f317218, v33
	v_fma_f32 v70, v236, s49, v17
	v_fma_f32 v71, v237, s49, v70
	v_fma_f32 v72, v238, s49, v71
	v_fma_f32 v73, v239, s49, v72
	v_fma_f32 v74, v106, s49, v73
	v_fma_f32 v75, v107, s49, v74
	v_fma_f32 v76, v108, s49, v75
	v_fma_f32 v77, v109, s49, v76
	v_fma_f32 v78, v240, s49, v77
	v_fma_f32 v79, v241, s49, v78
	v_fma_f32 v80, v242, s49, v79
	v_fma_f32 v81, v243, s49, v80
	v_fma_f32 v82, v110, s49, v81
	v_fma_f32 v83, v111, s49, v82
	v_fma_f32 v84, v112, s49, v83
	v_fma_f32 v85, v113, s49, v84
	v_mov_b32_e32 v17, v85
	s_waitcnt vmcnt(0)
; __device__ __forceinline__ unsigned f2bf(float f) { unsigned r; asm("v_cvt_pk_bf16_f32 %0, %1, %1" : "=v"(r) : "v"(f)); return r & 0xffffu; }
; __device__ __forceinline__ void gl1_item(PREF p, int l, int item, bool valid, LAS unsigned char* pl, int sw, int lane) {
;     ...
;                 for (int ss = 0; ss < 16; ++ss) { const int s = (g4 + 1) * 16 + ss; const int i = d ? 63 - s : s; const bf16_t* pr = P + (size_t)(row0 + i * rstride) * PW + h * 64 + lane;
;                     qn[ss] = __builtin_bit_cast(float, (unsigned)pr[1024]); kn[ss] = __builtin_bit_cast(float, (unsigned)pr[1280]); }
;                 __builtin_amdgcn_sched_barrier(0);
;             }
;             float gv[16];
; #pragma unroll
;             for (int ss = 0; ss < 16; ++ss) { const int s = g4 * 16 + ss; const int i = d ? 63 - s : s;
;                 float z = bup;
; #pragma unroll
;                 for (int r2 = 0; r2 < 8; ++r2) { const unsigned w = (unsigned)__builtin_amdgcn_readlane((int)lrp[r2], i);
;                     z = __builtin_amdgcn_fdot2_f32_bf16(__builtin_bit_cast(bf16x2_t, w), __builtin_bit_cast(bf16x2_t, wupp[r2]), z, false); }
;                 gv[ss] = -(fmaxf(-z, 0.f) + __logf(1.f + __expf(-fabsf(z)))) * (1.f / 16.f);
;                 __builtin_amdgcn_sched_barrier(0);
;             }
; #pragma unroll
;             for (int ss = 0; ss < 16; ++ss) { const int s = g4 * 16 + ss; const int i = d ? 63 - s : s; const size_t rowi = (size_t)(row0 + i * rstride);
;                 bc += gv[ss];
;                 const float en = __expf(-bc), ep = __expf(bc);
;                 const float kt = kc[ss] * en, qt = qc[ss] * 0.125f * ep;
;                 const unsigned ktb = f2bf(kt);
;                 sKt[lane * 72 + i] = (bf16_t)ktb;
;                 QK[rowi * 1024 + d * 512 + h * 64 + lane] = (bf16_t)f2bf(qt);
;                 QK[rowi * 1024 + d * 512 + 256 + h * 64 + lane] = (bf16_t)ktb;
	global_load_ushort v180, v134, s[6:7]
	global_load_ushort v196, v134, s[6:7] offset:512
	s_add_u32 s6, s6, s54
	s_addc_u32 s7, s7, s55
	global_load_ushort v181, v134, s[6:7]
	global_load_ushort v197, v134, s[6:7] offset:512
	s_add_u32 s6, s6, s54
	s_addc_u32 s7, s7, s55
	global_load_ushort v182, v134, s[6:7]
	global_load_ushort v198, v134, s[6:7] offset:512
	s_add_u32 s6, s6, s54
	s_addc_u32 s7, s7, s55
	global_load_ushort v183, v134, s[6:7]
	global_load_ushort v199, v134, s[6:7] offset:512
	s_add_u32 s6, s6, s54
	s_addc_u32 s7, s7, s55
	global_load_ushort v184, v134, s[6:7]
	global_load_ushort v200, v134, s[6:7] offset:512
	s_add_u32 s6, s6, s54
	s_addc_u32 s7, s7, s55
	global_load_ushort v185, v134, s[6:7]
	global_load_ushort v201, v134, s[6:7] offset:512
	s_add_u32 s6, s6, s54
	s_addc_u32 s7, s7, s55
	global_load_ushort v186, v134, s[6:7]
	global_load_ushort v202, v134, s[6:7] offset:512
	s_add_u32 s6, s6, s54
	s_addc_u32 s7, s7, s55
	global_load_ushort v187, v134, s[6:7]
	global_load_ushort v203, v134, s[6:7] offset:512
	s_add_u32 s6, s6, s54
	s_addc_u32 s7, s7, s55
	global_load_ushort v188, v134, s[6:7]
	global_load_ushort v204, v134, s[6:7] offset:512
	s_add_u32 s6, s6, s54
	s_addc_u32 s7, s7, s55
	global_load_ushort v189, v134, s[6:7]
	global_load_ushort v205, v134, s[6:7] offset:512
	s_add_u32 s6, s6, s54
	s_addc_u32 s7, s7, s55
	global_load_ushort v190, v134, s[6:7]
	global_load_ushort v206, v134, s[6:7] offset:512
	s_add_u32 s6, s6, s54
	s_addc_u32 s7, s7, s55
	global_load_ushort v191, v134, s[6:7]
	global_load_ushort v207, v134, s[6:7] offset:512
	s_add_u32 s6, s6, s54
	s_addc_u32 s7, s7, s55
	global_load_ushort v192, v134, s[6:7]
	global_load_ushort v208, v134, s[6:7] offset:512
	s_add_u32 s6, s6, s54
	s_addc_u32 s7, s7, s55
	global_load_ushort v193, v134, s[6:7]
	global_load_ushort v209, v134, s[6:7] offset:512
	s_add_u32 s6, s6, s54
	s_addc_u32 s7, s7, s55
	global_load_ushort v194, v134, s[6:7]
	global_load_ushort v210, v134, s[6:7] offset:512
	s_add_u32 s6, s6, s54
	s_addc_u32 s7, s7, s55
	global_load_ushort v195, v134, s[6:7]
	global_load_ushort v211, v134, s[6:7] offset:512
	s_add_u32 s6, s6, s54
	s_addc_u32 s7, s7, s55
	v_mul_f32_e32 v18, 0xbfb8aa3b, v70
	v_mul_f32_e32 v19, 0xbfb8aa3b, v71
	v_mul_f32_e32 v20, 0xbfb8aa3b, v72
	v_mul_f32_e32 v21, 0xbfb8aa3b, v73
	v_mul_f32_e32 v22, 0xbfb8aa3b, v74
	v_mul_f32_e32 v23, 0xbfb8aa3b, v75
	v_mul_f32_e32 v24, 0xbfb8aa3b, v76
	v_mul_f32_e32 v25, 0xbfb8aa3b, v77
	v_mul_f32_e32 v26, 0xbfb8aa3b, v78
	v_mul_f32_e32 v27, 0xbfb8aa3b, v79
	v_mul_f32_e32 v28, 0xbfb8aa3b, v80
	v_mul_f32_e32 v29, 0xbfb8aa3b, v81
	v_mul_f32_e32 v30, 0xbfb8aa3b, v82
	v_mul_f32_e32 v31, 0xbfb8aa3b, v83
	v_mul_f32_e32 v32, 0xbfb8aa3b, v84
	v_mul_f32_e32 v33, 0xbfb8aa3b, v85
	v_exp_f32_e64 v236, -v18
	v_exp_f32_e64 v237, -v19
	v_exp_f32_e64 v238, -v20
	v_exp_f32_e64 v239, -v21
	v_exp_f32_e64 v106, -v22
	v_exp_f32_e64 v107, -v23
	v_exp_f32_e64 v108, -v24
	v_exp_f32_e64 v109, -v25
	v_exp_f32_e64 v240, -v26
	v_exp_f32_e64 v241, -v27
	v_exp_f32_e64 v242, -v28
	v_exp_f32_e64 v243, -v29
	v_exp_f32_e64 v110, -v30
	v_exp_f32_e64 v111, -v31
	v_exp_f32_e64 v112, -v32
	v_exp_f32_e64 v113, -v33
	v_exp_f32_e32 v18, v18
	v_exp_f32_e32 v19, v19
	v_exp_f32_e32 v20, v20
	v_exp_f32_e32 v21, v21
	v_exp_f32_e32 v22, v22
	v_exp_f32_e32 v23, v23
	v_exp_f32_e32 v24, v24
	v_exp_f32_e32 v25, v25
	v_exp_f32_e32 v26, v26
	v_exp_f32_e32 v27, v27
	v_exp_f32_e32 v28, v28
	v_exp_f32_e32 v29, v29
	v_exp_f32_e32 v30, v30
	v_exp_f32_e32 v31, v31
	v_exp_f32_e32 v32, v32
	v_exp_f32_e32 v33, v33
	v_lshlrev_b32_e32 v164, 16, v164
	v_lshlrev_b32_e32 v165, 16, v165
	v_lshlrev_b32_e32 v166, 16, v166
	v_lshlrev_b32_e32 v167, 16, v167
	v_lshlrev_b32_e32 v168, 16, v168
	v_lshlrev_b32_e32 v169, 16, v169
	v_lshlrev_b32_e32 v170, 16, v170
	v_lshlrev_b32_e32 v171, 16, v171
	v_lshlrev_b32_e32 v172, 16, v172
	v_lshlrev_b32_e32 v173, 16, v173
	v_lshlrev_b32_e32 v174, 16, v174
	v_lshlrev_b32_e32 v175, 16, v175
	v_lshlrev_b32_e32 v176, 16, v176
	v_lshlrev_b32_e32 v177, 16, v177
	v_lshlrev_b32_e32 v178, 16, v178
	v_lshlrev_b32_e32 v179, 16, v179
	v_lshlrev_b32_e32 v148, 16, v148
	v_lshlrev_b32_e32 v149, 16, v149
	v_lshlrev_b32_e32 v150, 16, v150
	v_lshlrev_b32_e32 v151, 16, v151
	v_lshlrev_b32_e32 v152, 16, v152
	v_lshlrev_b32_e32 v153, 16, v153
	v_lshlrev_b32_e32 v154, 16, v154
	v_lshlrev_b32_e32 v155, 16, v155
	v_lshlrev_b32_e32 v156, 16, v156
	v_lshlrev_b32_e32 v157, 16, v157
	v_lshlrev_b32_e32 v158, 16, v158
	v_lshlrev_b32_e32 v159, 16, v159
	v_lshlrev_b32_e32 v160, 16, v160
	v_lshlrev_b32_e32 v161, 16, v161
	v_lshlrev_b32_e32 v162, 16, v162
	v_lshlrev_b32_e32 v163, 16, v163
	v_mul_f32_e32 v18, v18, v164
	v_mul_f32_e32 v19, v19, v165
	v_mul_f32_e32 v20, v20, v166
	v_mul_f32_e32 v21, v21, v167
	v_mul_f32_e32 v22, v22, v168
	v_mul_f32_e32 v23, v23, v169
	v_mul_f32_e32 v24, v24, v170
	v_mul_f32_e32 v25, v25, v171
	v_mul_f32_e32 v26, v26, v172
	v_mul_f32_e32 v27, v27, v173
	v_mul_f32_e32 v28, v28, v174
	v_mul_f32_e32 v29, v29, v175
	v_mul_f32_e32 v30, v30, v176
	v_mul_f32_e32 v31, v31, v177
	v_mul_f32_e32 v32, v32, v178
	v_mul_f32_e32 v33, v33, v179
	v_mul_f32_e32 v70, 0x3e000000, v148
	v_mul_f32_e32 v71, 0x3e000000, v149
	v_mul_f32_e32 v72, 0x3e000000, v150
	v_mul_f32_e32 v73, 0x3e000000, v151
	v_mul_f32_e32 v74, 0x3e000000, v152
	v_mul_f32_e32 v75, 0x3e000000, v153
	v_mul_f32_e32 v76, 0x3e000000, v154
	v_mul_f32_e32 v77, 0x3e000000, v155
	v_mul_f32_e32 v78, 0x3e000000, v156
	v_mul_f32_e32 v79, 0x3e000000, v157
	v_mul_f32_e32 v80, 0x3e000000, v158
	v_mul_f32_e32 v81, 0x3e000000, v159
	v_mul_f32_e32 v82, 0x3e000000, v160
	v_mul_f32_e32 v83, 0x3e000000, v161
; __device__ __forceinline__ unsigned f2bf(float f) { unsigned r; asm("v_cvt_pk_bf16_f32 %0, %1, %1" : "=v"(r) : "v"(f)); return r & 0xffffu; }
; __device__ __forceinline__ void gl1_item(PREF p, int l, int item, bool valid, LAS unsigned char* pl, int sw, int lane) {
;     ...
;             for (int ss = 0; ss < 16; ++ss) { const int s = g4 * 16 + ss; const int i = d ? 63 - s : s;
;                 float z = bup;
; #pragma unroll
;                 for (int r2 = 0; r2 < 8; ++r2) { const unsigned w = (unsigned)__builtin_amdgcn_readlane((int)lrp[r2], i);
;                     z = __builtin_amdgcn_fdot2_f32_bf16(__builtin_bit_cast(bf16x2_t, w), __builtin_bit_cast(bf16x2_t, wupp[r2]), z, false); }
;                 gv[ss] = -(fmaxf(-z, 0.f) + __logf(1.f + __expf(-fabsf(z)))) * (1.f / 16.f);
;     ...
;             for (int ss = 0; ss < 16; ++ss) { const int s = g4 * 16 + ss; const int i = d ? 63 - s : s; const size_t rowi = (size_t)(row0 + i * rstride);
;                 bc += gv[ss];
;                 const float en = __expf(-bc), ep = __expf(bc);
;                 const float kt = kc[ss] * en, qt = qc[ss] * 0.125f * ep;
;                 const unsigned ktb = f2bf(kt);
;                 sKt[lane * 72 + i] = (bf16_t)ktb;
;                 QK[rowi * 1024 + d * 512 + h * 64 + lane] = (bf16_t)f2bf(qt);
;                 QK[rowi * 1024 + d * 512 + 256 + h * 64 + lane] = (bf16_t)ktb;
;             }
	v_mul_f32_e32 v84, 0x3e000000, v162
	v_mul_f32_e32 v85, 0x3e000000, v163
	v_mul_f32_e32 v236, v70, v236
	v_mul_f32_e32 v237, v71, v237
	v_mul_f32_e32 v238, v72, v238
	v_mul_f32_e32 v239, v73, v239
	v_mul_f32_e32 v106, v74, v106
	v_mul_f32_e32 v107, v75, v107
	v_mul_f32_e32 v108, v76, v108
	v_mul_f32_e32 v109, v77, v109
	v_mul_f32_e32 v240, v78, v240
	v_mul_f32_e32 v241, v79, v241
	v_mul_f32_e32 v242, v80, v242
	v_mul_f32_e32 v243, v81, v243
	v_mul_f32_e32 v110, v82, v110
	v_mul_f32_e32 v111, v83, v111
	v_mul_f32_e32 v112, v84, v112
	v_mul_f32_e32 v113, v85, v113
	v_cvt_pk_bf16_f32 v18, v18, v236
	v_cvt_pk_bf16_f32 v19, v19, v237
	v_cvt_pk_bf16_f32 v20, v20, v238
	v_cvt_pk_bf16_f32 v21, v21, v239
	v_cvt_pk_bf16_f32 v22, v22, v106
	v_cvt_pk_bf16_f32 v23, v23, v107
	v_cvt_pk_bf16_f32 v24, v24, v108
	v_cvt_pk_bf16_f32 v25, v25, v109
	v_cvt_pk_bf16_f32 v26, v26, v240
	v_cvt_pk_bf16_f32 v27, v27, v241
	v_cvt_pk_bf16_f32 v28, v28, v242
	v_cvt_pk_bf16_f32 v29, v29, v243
	v_cvt_pk_bf16_f32 v30, v30, v110
	v_cvt_pk_bf16_f32 v31, v31, v111
	v_cvt_pk_bf16_f32 v32, v32, v112
	v_cvt_pk_bf16_f32 v33, v33, v113
	ds_write_b16 v60, v18
	v_add_u32_e32 v60, v61, v60
	global_store_short_d16_hi v134, v18, s[4:5]
	global_store_short v134, v18, s[4:5] offset:512
	s_add_u32 s4, s4, s56
	s_addc_u32 s5, s5, s3
	ds_write_b16 v60, v19
	v_add_u32_e32 v60, v61, v60
	global_store_short_d16_hi v134, v19, s[4:5]
	global_store_short v134, v19, s[4:5] offset:512
	s_add_u32 s4, s4, s56
	s_addc_u32 s5, s5, s3
	ds_write_b16 v60, v20
	v_add_u32_e32 v60, v61, v60
	global_store_short_d16_hi v134, v20, s[4:5]
	global_store_short v134, v20, s[4:5] offset:512
	s_add_u32 s4, s4, s56
	s_addc_u32 s5, s5, s3
	ds_write_b16 v60, v21
	v_add_u32_e32 v60, v61, v60
	global_store_short_d16_hi v134, v21, s[4:5]
	global_store_short v134, v21, s[4:5] offset:512
	s_add_u32 s4, s4, s56
	s_addc_u32 s5, s5, s3
	ds_write_b16 v60, v22
	v_add_u32_e32 v60, v61, v60
	global_store_short_d16_hi v134, v22, s[4:5]
	global_store_short v134, v22, s[4:5] offset:512
	s_add_u32 s4, s4, s56
	s_addc_u32 s5, s5, s3
	ds_write_b16 v60, v23
	v_add_u32_e32 v60, v61, v60
	global_store_short_d16_hi v134, v23, s[4:5]
	global_store_short v134, v23, s[4:5] offset:512
	s_add_u32 s4, s4, s56
	s_addc_u32 s5, s5, s3
	ds_write_b16 v60, v24
	v_add_u32_e32 v60, v61, v60
	global_store_short_d16_hi v134, v24, s[4:5]
	global_store_short v134, v24, s[4:5] offset:512
	s_add_u32 s4, s4, s56
	s_addc_u32 s5, s5, s3
	ds_write_b16 v60, v25
	v_add_u32_e32 v60, v61, v60
	global_store_short_d16_hi v134, v25, s[4:5]
	global_store_short v134, v25, s[4:5] offset:512
	s_add_u32 s4, s4, s56
	s_addc_u32 s5, s5, s3
	ds_write_b16 v60, v26
	v_add_u32_e32 v60, v61, v60
	global_store_short_d16_hi v134, v26, s[4:5]
	global_store_short v134, v26, s[4:5] offset:512
	s_add_u32 s4, s4, s56
	s_addc_u32 s5, s5, s3
	ds_write_b16 v60, v27
	v_add_u32_e32 v60, v61, v60
	global_store_short_d16_hi v134, v27, s[4:5]
	global_store_short v134, v27, s[4:5] offset:512
	s_add_u32 s4, s4, s56
	s_addc_u32 s5, s5, s3
	ds_write_b16 v60, v28
	v_add_u32_e32 v60, v61, v60
	global_store_short_d16_hi v134, v28, s[4:5]
	global_store_short v134, v28, s[4:5] offset:512
	s_add_u32 s4, s4, s56
	s_addc_u32 s5, s5, s3
	ds_write_b16 v60, v29
	v_add_u32_e32 v60, v61, v60
	global_store_short_d16_hi v134, v29, s[4:5]
	global_store_short v134, v29, s[4:5] offset:512
	s_add_u32 s4, s4, s56
	s_addc_u32 s5, s5, s3
	ds_write_b16 v60, v30
	v_add_u32_e32 v60, v61, v60
	global_store_short_d16_hi v134, v30, s[4:5]
	global_store_short v134, v30, s[4:5] offset:512
	s_add_u32 s4, s4, s56
	s_addc_u32 s5, s5, s3
	ds_write_b16 v60, v31
	v_add_u32_e32 v60, v61, v60
	global_store_short_d16_hi v134, v31, s[4:5]
	global_store_short v134, v31, s[4:5] offset:512
	s_add_u32 s4, s4, s56
	s_addc_u32 s5, s5, s3
	ds_write_b16 v60, v32
	v_add_u32_e32 v60, v61, v60
	global_store_short_d16_hi v134, v32, s[4:5]
	global_store_short v134, v32, s[4:5] offset:512
	s_add_u32 s4, s4, s56
	s_addc_u32 s5, s5, s3
	ds_write_b16 v60, v33
	v_add_u32_e32 v60, v61, v60
	global_store_short_d16_hi v134, v33, s[4:5]
	global_store_short v134, v33, s[4:5] offset:512
	s_add_u32 s4, s4, s56
	s_addc_u32 s5, s5, s3
	v_mul_f32_e64 v18, |v244|, s1
	v_mul_f32_e64 v19, |v245|, s1
	v_mul_f32_e64 v20, |v246|, s1
	v_mul_f32_e64 v21, |v247|, s1
	v_mul_f32_e64 v22, |v114|, s1
	v_mul_f32_e64 v23, |v115|, s1
	v_mul_f32_e64 v24, |v116|, s1
	v_mul_f32_e64 v25, |v117|, s1
	v_mul_f32_e64 v26, |v248|, s1
	v_mul_f32_e64 v27, |v249|, s1
	v_mul_f32_e64 v28, |v250|, s1
	v_mul_f32_e64 v29, |v251|, s1
	v_mul_f32_e64 v30, |v118|, s1
	v_mul_f32_e64 v31, |v119|, s1
	v_mul_f32_e64 v32, |v120|, s1
	v_mul_f32_e64 v33, |v121|, s1
	v_exp_f32_e32 v18, v18
	v_exp_f32_e32 v19, v19
	v_exp_f32_e32 v20, v20
	v_exp_f32_e32 v21, v21
	v_exp_f32_e32 v22, v22
	v_exp_f32_e32 v23, v23
	v_exp_f32_e32 v24, v24
	v_exp_f32_e32 v25, v25
	v_exp_f32_e32 v26, v26
	v_exp_f32_e32 v27, v27
	v_exp_f32_e32 v28, v28
	v_exp_f32_e32 v29, v29
	v_exp_f32_e32 v30, v30
	v_exp_f32_e32 v31, v31
	v_exp_f32_e32 v32, v32
	v_exp_f32_e32 v33, v33
	v_max_f32_e64 v244, -v244, 0
	v_max_f32_e64 v245, -v245, 0
	v_max_f32_e64 v246, -v246, 0
	v_max_f32_e64 v247, -v247, 0
	v_max_f32_e64 v114, -v114, 0
	v_max_f32_e64 v115, -v115, 0
	v_max_f32_e64 v116, -v116, 0
	v_max_f32_e64 v117, -v117, 0
	v_max_f32_e64 v248, -v248, 0
	v_max_f32_e64 v249, -v249, 0
	v_max_f32_e64 v250, -v250, 0
	v_max_f32_e64 v251, -v251, 0
	v_max_f32_e64 v118, -v118, 0
	v_max_f32_e64 v119, -v119, 0
	v_max_f32_e64 v120, -v120, 0
	v_max_f32_e64 v121, -v121, 0
	v_add_f32_e32 v18, 1.0, v18
	v_add_f32_e32 v19, 1.0, v19
	v_add_f32_e32 v20, 1.0, v20
; __device__ __forceinline__ unsigned f2bf(float f) { unsigned r; asm("v_cvt_pk_bf16_f32 %0, %1, %1" : "=v"(r) : "v"(f)); return r & 0xffffu; }
; __device__ __forceinline__ void gl1_item(PREF p, int l, int item, bool valid, LAS unsigned char* pl, int sw, int lane) {
;     ...
;             for (int ss = 0; ss < 16; ++ss) { const int s = g4 * 16 + ss; const int i = d ? 63 - s : s;
;                 float z = bup;
; #pragma unroll
;                 for (int r2 = 0; r2 < 8; ++r2) { const unsigned w = (unsigned)__builtin_amdgcn_readlane((int)lrp[r2], i);
;                     z = __builtin_amdgcn_fdot2_f32_bf16(__builtin_bit_cast(bf16x2_t, w), __builtin_bit_cast(bf16x2_t, wupp[r2]), z, false); }
;                 gv[ss] = -(fmaxf(-z, 0.f) + __logf(1.f + __expf(-fabsf(z)))) * (1.f / 16.f);
;                 __builtin_amdgcn_sched_barrier(0);
;             }
; #pragma unroll
;             for (int ss = 0; ss < 16; ++ss) { const int s = g4 * 16 + ss; const int i = d ? 63 - s : s; const size_t rowi = (size_t)(row0 + i * rstride);
;                 bc += gv[ss];
;                 const float en = __expf(-bc), ep = __expf(bc);
;                 const float kt = kc[ss] * en, qt = qc[ss] * 0.125f * ep;
;                 const unsigned ktb = f2bf(kt);
;                 sKt[lane * 72 + i] = (bf16_t)ktb;
;                 QK[rowi * 1024 + d * 512 + h * 64 + lane] = (bf16_t)f2bf(qt);
;                 QK[rowi * 1024 + d * 512 + 256 + h * 64 + lane] = (bf16_t)ktb;
;             }
; #pragma unroll
;             for (int ss = 0; ss < 16; ++ss) { qc[ss] = bf2f(__builtin_bit_cast(unsigned, qn[ss])); kc[ss] = bf2f(__builtin_bit_cast(unsigned, kn[ss])); }
	v_add_f32_e32 v21, 1.0, v21
	v_add_f32_e32 v22, 1.0, v22
	v_add_f32_e32 v23, 1.0, v23
	v_add_f32_e32 v24, 1.0, v24
	v_add_f32_e32 v25, 1.0, v25
	v_add_f32_e32 v26, 1.0, v26
	v_add_f32_e32 v27, 1.0, v27
	v_add_f32_e32 v28, 1.0, v28
	v_add_f32_e32 v29, 1.0, v29
	v_add_f32_e32 v30, 1.0, v30
	v_add_f32_e32 v31, 1.0, v31
	v_add_f32_e32 v32, 1.0, v32
	v_add_f32_e32 v33, 1.0, v33
	v_log_f32_e32 v18, v18
	v_log_f32_e32 v19, v19
	v_log_f32_e32 v20, v20
	v_log_f32_e32 v21, v21
	v_log_f32_e32 v22, v22
	v_log_f32_e32 v23, v23
	v_log_f32_e32 v24, v24
	v_log_f32_e32 v25, v25
	v_log_f32_e32 v26, v26
	v_log_f32_e32 v27, v27
	v_log_f32_e32 v28, v28
	v_log_f32_e32 v29, v29
	v_log_f32_e32 v30, v30
	v_log_f32_e32 v31, v31
	v_log_f32_e32 v32, v32
	v_log_f32_e32 v33, v33
	v_fmac_f32_e32 v244, 0x3f317218, v18
	v_fmac_f32_e32 v245, 0x3f317218, v19
	v_fmac_f32_e32 v246, 0x3f317218, v20
	v_fmac_f32_e32 v247, 0x3f317218, v21
	v_fmac_f32_e32 v114, 0x3f317218, v22
	v_fmac_f32_e32 v115, 0x3f317218, v23
	v_fmac_f32_e32 v116, 0x3f317218, v24
	v_fmac_f32_e32 v117, 0x3f317218, v25
	v_fmac_f32_e32 v248, 0x3f317218, v26
	v_fmac_f32_e32 v249, 0x3f317218, v27
	v_fmac_f32_e32 v250, 0x3f317218, v28
	v_fmac_f32_e32 v251, 0x3f317218, v29
	v_fmac_f32_e32 v118, 0x3f317218, v30
	v_fmac_f32_e32 v119, 0x3f317218, v31
	v_fmac_f32_e32 v120, 0x3f317218, v32
	v_fmac_f32_e32 v121, 0x3f317218, v33
	v_fma_f32 v70, v244, s49, v17
	v_fma_f32 v71, v245, s49, v70
	v_fma_f32 v72, v246, s49, v71
	v_fma_f32 v73, v247, s49, v72
	v_fma_f32 v74, v114, s49, v73
	v_fma_f32 v75, v115, s49, v74
	v_fma_f32 v76, v116, s49, v75
	v_fma_f32 v77, v117, s49, v76
	v_fma_f32 v78, v248, s49, v77
	v_fma_f32 v79, v249, s49, v78
	v_fma_f32 v80, v250, s49, v79
	v_fma_f32 v81, v251, s49, v80
	v_fma_f32 v82, v118, s49, v81
	v_fma_f32 v83, v119, s49, v82
	v_fma_f32 v84, v120, s49, v83
	v_fma_f32 v85, v121, s49, v84
	v_mov_b32_e32 v17, v85
	s_waitcnt vmcnt(32)
	global_load_short_d16_hi v148, v134, s[6:7]
	global_load_short_d16_hi v164, v134, s[6:7] offset:512
	s_add_u32 s6, s6, s54
	s_addc_u32 s7, s7, s55
	global_load_short_d16_hi v149, v134, s[6:7]
	global_load_short_d16_hi v165, v134, s[6:7] offset:512
	s_add_u32 s6, s6, s54
	s_addc_u32 s7, s7, s55
	global_load_short_d16_hi v150, v134, s[6:7]
	global_load_short_d16_hi v166, v134, s[6:7] offset:512
	s_add_u32 s6, s6, s54
	s_addc_u32 s7, s7, s55
	global_load_short_d16_hi v151, v134, s[6:7]
	global_load_short_d16_hi v167, v134, s[6:7] offset:512
	s_add_u32 s6, s6, s54
	s_addc_u32 s7, s7, s55
	global_load_short_d16_hi v152, v134, s[6:7]
	global_load_short_d16_hi v168, v134, s[6:7] offset:512
	s_add_u32 s6, s6, s54
	s_addc_u32 s7, s7, s55
	global_load_short_d16_hi v153, v134, s[6:7]
	global_load_short_d16_hi v169, v134, s[6:7] offset:512
	s_add_u32 s6, s6, s54
	s_addc_u32 s7, s7, s55
	global_load_short_d16_hi v154, v134, s[6:7]
	global_load_short_d16_hi v170, v134, s[6:7] offset:512
	s_add_u32 s6, s6, s54
	s_addc_u32 s7, s7, s55
	global_load_short_d16_hi v155, v134, s[6:7]
	global_load_short_d16_hi v171, v134, s[6:7] offset:512
	s_add_u32 s6, s6, s54
	s_addc_u32 s7, s7, s55
	global_load_short_d16_hi v156, v134, s[6:7]
	global_load_short_d16_hi v172, v134, s[6:7] offset:512
	s_add_u32 s6, s6, s54
	s_addc_u32 s7, s7, s55
	global_load_short_d16_hi v157, v134, s[6:7]
	global_load_short_d16_hi v173, v134, s[6:7] offset:512
	s_add_u32 s6, s6, s54
	s_addc_u32 s7, s7, s55
	global_load_short_d16_hi v158, v134, s[6:7]
	global_load_short_d16_hi v174, v134, s[6:7] offset:512
	s_add_u32 s6, s6, s54
	s_addc_u32 s7, s7, s55
	global_load_short_d16_hi v159, v134, s[6:7]
	global_load_short_d16_hi v175, v134, s[6:7] offset:512
	s_add_u32 s6, s6, s54
	s_addc_u32 s7, s7, s55
	global_load_short_d16_hi v160, v134, s[6:7]
	global_load_short_d16_hi v176, v134, s[6:7] offset:512
	s_add_u32 s6, s6, s54
	s_addc_u32 s7, s7, s55
	global_load_short_d16_hi v161, v134, s[6:7]
	global_load_short_d16_hi v177, v134, s[6:7] offset:512
	s_add_u32 s6, s6, s54
	s_addc_u32 s7, s7, s55
	global_load_short_d16_hi v162, v134, s[6:7]
	global_load_short_d16_hi v178, v134, s[6:7] offset:512
	s_add_u32 s6, s6, s54
	s_addc_u32 s7, s7, s55
	global_load_short_d16_hi v163, v134, s[6:7]
	global_load_short_d16_hi v179, v134, s[6:7] offset:512
	s_add_u32 s6, s6, s54
	s_addc_u32 s7, s7, s55
	v_mul_f32_e32 v18, 0xbfb8aa3b, v70
	v_mul_f32_e32 v19, 0xbfb8aa3b, v71
	v_mul_f32_e32 v20, 0xbfb8aa3b, v72
	v_mul_f32_e32 v21, 0xbfb8aa3b, v73
	v_mul_f32_e32 v22, 0xbfb8aa3b, v74
	v_mul_f32_e32 v23, 0xbfb8aa3b, v75
	v_mul_f32_e32 v24, 0xbfb8aa3b, v76
	v_mul_f32_e32 v25, 0xbfb8aa3b, v77
	v_mul_f32_e32 v26, 0xbfb8aa3b, v78
	v_mul_f32_e32 v27, 0xbfb8aa3b, v79
	v_mul_f32_e32 v28, 0xbfb8aa3b, v80
	v_mul_f32_e32 v29, 0xbfb8aa3b, v81
	v_mul_f32_e32 v30, 0xbfb8aa3b, v82
	v_mul_f32_e32 v31, 0xbfb8aa3b, v83
	v_mul_f32_e32 v32, 0xbfb8aa3b, v84
	v_mul_f32_e32 v33, 0xbfb8aa3b, v85
	v_exp_f32_e64 v244, -v18
	v_exp_f32_e64 v245, -v19
	v_exp_f32_e64 v246, -v20
	v_exp_f32_e64 v247, -v21
	v_exp_f32_e64 v114, -v22
	v_exp_f32_e64 v115, -v23
	v_exp_f32_e64 v116, -v24
	v_exp_f32_e64 v117, -v25
	v_exp_f32_e64 v248, -v26
	v_exp_f32_e64 v249, -v27
	v_exp_f32_e64 v250, -v28
	v_exp_f32_e64 v251, -v29
	v_exp_f32_e64 v118, -v30
	v_exp_f32_e64 v119, -v31
	v_exp_f32_e64 v120, -v32
	v_exp_f32_e64 v121, -v33
	v_exp_f32_e32 v18, v18
	v_exp_f32_e32 v19, v19
	v_exp_f32_e32 v20, v20
	v_exp_f32_e32 v21, v21
	v_exp_f32_e32 v22, v22
	v_exp_f32_e32 v23, v23
	v_exp_f32_e32 v24, v24
	v_exp_f32_e32 v25, v25
	v_exp_f32_e32 v26, v26
	v_exp_f32_e32 v27, v27
	v_exp_f32_e32 v28, v28
	v_exp_f32_e32 v29, v29
	v_exp_f32_e32 v30, v30
	v_exp_f32_e32 v31, v31
	v_exp_f32_e32 v32, v32
; __device__ __forceinline__ unsigned f2bf(float f) { unsigned r; asm("v_cvt_pk_bf16_f32 %0, %1, %1" : "=v"(r) : "v"(f)); return r & 0xffffu; }
; __device__ __forceinline__ void gl1_item(PREF p, int l, int item, bool valid, LAS unsigned char* pl, int sw, int lane) {
;     ...
;             for (int ss = 0; ss < 16; ++ss) { const int s = g4 * 16 + ss; const int i = d ? 63 - s : s; const size_t rowi = (size_t)(row0 + i * rstride);
;                 bc += gv[ss];
;                 const float en = __expf(-bc), ep = __expf(bc);
;                 const float kt = kc[ss] * en, qt = qc[ss] * 0.125f * ep;
;                 const unsigned ktb = f2bf(kt);
;                 sKt[lane * 72 + i] = (bf16_t)ktb;
;                 QK[rowi * 1024 + d * 512 + h * 64 + lane] = (bf16_t)f2bf(qt);
;                 QK[rowi * 1024 + d * 512 + 256 + h * 64 + lane] = (bf16_t)ktb;
;             }
	v_exp_f32_e32 v33, v33
	v_lshlrev_b32_e32 v196, 16, v196
	v_lshlrev_b32_e32 v197, 16, v197
	v_lshlrev_b32_e32 v198, 16, v198
	v_lshlrev_b32_e32 v199, 16, v199
	v_lshlrev_b32_e32 v200, 16, v200
	v_lshlrev_b32_e32 v201, 16, v201
	v_lshlrev_b32_e32 v202, 16, v202
	v_lshlrev_b32_e32 v203, 16, v203
	v_lshlrev_b32_e32 v204, 16, v204
	v_lshlrev_b32_e32 v205, 16, v205
	v_lshlrev_b32_e32 v206, 16, v206
	v_lshlrev_b32_e32 v207, 16, v207
	v_lshlrev_b32_e32 v208, 16, v208
	v_lshlrev_b32_e32 v209, 16, v209
	v_lshlrev_b32_e32 v210, 16, v210
	v_lshlrev_b32_e32 v211, 16, v211
	v_lshlrev_b32_e32 v180, 16, v180
	v_lshlrev_b32_e32 v181, 16, v181
	v_lshlrev_b32_e32 v182, 16, v182
	v_lshlrev_b32_e32 v183, 16, v183
	v_lshlrev_b32_e32 v184, 16, v184
	v_lshlrev_b32_e32 v185, 16, v185
	v_lshlrev_b32_e32 v186, 16, v186
	v_lshlrev_b32_e32 v187, 16, v187
	v_lshlrev_b32_e32 v188, 16, v188
	v_lshlrev_b32_e32 v189, 16, v189
	v_lshlrev_b32_e32 v190, 16, v190
	v_lshlrev_b32_e32 v191, 16, v191
	v_lshlrev_b32_e32 v192, 16, v192
	v_lshlrev_b32_e32 v193, 16, v193
	v_lshlrev_b32_e32 v194, 16, v194
	v_lshlrev_b32_e32 v195, 16, v195
	v_mul_f32_e32 v18, v18, v196
	v_mul_f32_e32 v19, v19, v197
	v_mul_f32_e32 v20, v20, v198
	v_mul_f32_e32 v21, v21, v199
	v_mul_f32_e32 v22, v22, v200
	v_mul_f32_e32 v23, v23, v201
	v_mul_f32_e32 v24, v24, v202
	v_mul_f32_e32 v25, v25, v203
	v_mul_f32_e32 v26, v26, v204
	v_mul_f32_e32 v27, v27, v205
	v_mul_f32_e32 v28, v28, v206
	v_mul_f32_e32 v29, v29, v207
	v_mul_f32_e32 v30, v30, v208
	v_mul_f32_e32 v31, v31, v209
	v_mul_f32_e32 v32, v32, v210
	v_mul_f32_e32 v33, v33, v211
	v_mul_f32_e32 v70, 0x3e000000, v180
	v_mul_f32_e32 v71, 0x3e000000, v181
	v_mul_f32_e32 v72, 0x3e000000, v182
	v_mul_f32_e32 v73, 0x3e000000, v183
	v_mul_f32_e32 v74, 0x3e000000, v184
	v_mul_f32_e32 v75, 0x3e000000, v185
	v_mul_f32_e32 v76, 0x3e000000, v186
	v_mul_f32_e32 v77, 0x3e000000, v187
	v_mul_f32_e32 v78, 0x3e000000, v188
	v_mul_f32_e32 v79, 0x3e000000, v189
	v_mul_f32_e32 v80, 0x3e000000, v190
	v_mul_f32_e32 v81, 0x3e000000, v191
	v_mul_f32_e32 v82, 0x3e000000, v192
	v_mul_f32_e32 v83, 0x3e000000, v193
	v_mul_f32_e32 v84, 0x3e000000, v194
	v_mul_f32_e32 v85, 0x3e000000, v195
	v_mul_f32_e32 v244, v70, v244
	v_mul_f32_e32 v245, v71, v245
	v_mul_f32_e32 v246, v72, v246
	v_mul_f32_e32 v247, v73, v247
	v_mul_f32_e32 v114, v74, v114
	v_mul_f32_e32 v115, v75, v115
	v_mul_f32_e32 v116, v76, v116
	v_mul_f32_e32 v117, v77, v117
	v_mul_f32_e32 v248, v78, v248
	v_mul_f32_e32 v249, v79, v249
	v_mul_f32_e32 v250, v80, v250
	v_mul_f32_e32 v251, v81, v251
	v_mul_f32_e32 v118, v82, v118
	v_mul_f32_e32 v119, v83, v119
	v_mul_f32_e32 v120, v84, v120
	v_mul_f32_e32 v121, v85, v121
	v_cvt_pk_bf16_f32 v18, v18, v244
	v_cvt_pk_bf16_f32 v19, v19, v245
	v_cvt_pk_bf16_f32 v20, v20, v246
	v_cvt_pk_bf16_f32 v21, v21, v247
	v_cvt_pk_bf16_f32 v22, v22, v114
	v_cvt_pk_bf16_f32 v23, v23, v115
	v_cvt_pk_bf16_f32 v24, v24, v116
	v_cvt_pk_bf16_f32 v25, v25, v117
	v_cvt_pk_bf16_f32 v26, v26, v248
	v_cvt_pk_bf16_f32 v27, v27, v249
	v_cvt_pk_bf16_f32 v28, v28, v250
	v_cvt_pk_bf16_f32 v29, v29, v251
	v_cvt_pk_bf16_f32 v30, v30, v118
	v_cvt_pk_bf16_f32 v31, v31, v119
	v_cvt_pk_bf16_f32 v32, v32, v120
	v_cvt_pk_bf16_f32 v33, v33, v121
	ds_write_b16 v60, v18
	v_add_u32_e32 v60, v61, v60
	global_store_short_d16_hi v134, v18, s[4:5]
	global_store_short v134, v18, s[4:5] offset:512
	s_add_u32 s4, s4, s56
	s_addc_u32 s5, s5, s3
	ds_write_b16 v60, v19
	v_add_u32_e32 v60, v61, v60
	global_store_short_d16_hi v134, v19, s[4:5]
	global_store_short v134, v19, s[4:5] offset:512
	s_add_u32 s4, s4, s56
	s_addc_u32 s5, s5, s3
	ds_write_b16 v60, v20
	v_add_u32_e32 v60, v61, v60
	global_store_short_d16_hi v134, v20, s[4:5]
	global_store_short v134, v20, s[4:5] offset:512
	s_add_u32 s4, s4, s56
	s_addc_u32 s5, s5, s3
	ds_write_b16 v60, v21
	v_add_u32_e32 v60, v61, v60
	global_store_short_d16_hi v134, v21, s[4:5]
	global_store_short v134, v21, s[4:5] offset:512
	s_add_u32 s4, s4, s56
	s_addc_u32 s5, s5, s3
	ds_write_b16 v60, v22
	v_add_u32_e32 v60, v61, v60
	global_store_short_d16_hi v134, v22, s[4:5]
	global_store_short v134, v22, s[4:5] offset:512
	s_add_u32 s4, s4, s56
	s_addc_u32 s5, s5, s3
	ds_write_b16 v60, v23
	v_add_u32_e32 v60, v61, v60
	global_store_short_d16_hi v134, v23, s[4:5]
	global_store_short v134, v23, s[4:5] offset:512
	s_add_u32 s4, s4, s56
	s_addc_u32 s5, s5, s3
	ds_write_b16 v60, v24
	v_add_u32_e32 v60, v61, v60
	global_store_short_d16_hi v134, v24, s[4:5]
	global_store_short v134, v24, s[4:5] offset:512
	s_add_u32 s4, s4, s56
	s_addc_u32 s5, s5, s3
	ds_write_b16 v60, v25
	v_add_u32_e32 v60, v61, v60
	global_store_short_d16_hi v134, v25, s[4:5]
	global_store_short v134, v25, s[4:5] offset:512
	s_add_u32 s4, s4, s56
	s_addc_u32 s5, s5, s3
	ds_write_b16 v60, v26
	v_add_u32_e32 v60, v61, v60
	global_store_short_d16_hi v134, v26, s[4:5]
	global_store_short v134, v26, s[4:5] offset:512
	s_add_u32 s4, s4, s56
	s_addc_u32 s5, s5, s3
	ds_write_b16 v60, v27
	v_add_u32_e32 v60, v61, v60
	global_store_short_d16_hi v134, v27, s[4:5]
	global_store_short v134, v27, s[4:5] offset:512
	s_add_u32 s4, s4, s56
	s_addc_u32 s5, s5, s3
	ds_write_b16 v60, v28
	v_add_u32_e32 v60, v61, v60
	global_store_short_d16_hi v134, v28, s[4:5]
	global_store_short v134, v28, s[4:5] offset:512
	s_add_u32 s4, s4, s56
	s_addc_u32 s5, s5, s3
	ds_write_b16 v60, v29
	v_add_u32_e32 v60, v61, v60
	global_store_short_d16_hi v134, v29, s[4:5]
	global_store_short v134, v29, s[4:5] offset:512
	s_add_u32 s4, s4, s56
	s_addc_u32 s5, s5, s3
	ds_write_b16 v60, v30
	v_add_u32_e32 v60, v61, v60
	global_store_short_d16_hi v134, v30, s[4:5]
; __device__ __forceinline__ void gl1_item(PREF p, int l, int item, bool valid, LAS unsigned char* pl, int sw, int lane) {
;     ...
;             float gv[16];
; #pragma unroll
;             for (int ss = 0; ss < 16; ++ss) { const int s = g4 * 16 + ss; const int i = d ? 63 - s : s;
;                 float z = bup;
; #pragma unroll
;                 for (int r2 = 0; r2 < 8; ++r2) { const unsigned w = (unsigned)__builtin_amdgcn_readlane((int)lrp[r2], i);
;                     z = __builtin_amdgcn_fdot2_f32_bf16(__builtin_bit_cast(bf16x2_t, w), __builtin_bit_cast(bf16x2_t, wupp[r2]), z, false); }
;                 gv[ss] = -(fmaxf(-z, 0.f) + __logf(1.f + __expf(-fabsf(z)))) * (1.f / 16.f);
;                 __builtin_amdgcn_sched_barrier(0);
;             }
	global_store_short v134, v30, s[4:5] offset:512
	s_add_u32 s4, s4, s56
	s_addc_u32 s5, s5, s3
	ds_write_b16 v60, v31
	v_add_u32_e32 v60, v61, v60
	global_store_short_d16_hi v134, v31, s[4:5]
	global_store_short v134, v31, s[4:5] offset:512
	s_add_u32 s4, s4, s56
	s_addc_u32 s5, s5, s3
	ds_write_b16 v60, v32
	v_add_u32_e32 v60, v61, v60
	global_store_short_d16_hi v134, v32, s[4:5]
	global_store_short v134, v32, s[4:5] offset:512
	s_add_u32 s4, s4, s56
	s_addc_u32 s5, s5, s3
	ds_write_b16 v60, v33
	v_add_u32_e32 v60, v61, v60
	global_store_short_d16_hi v134, v33, s[4:5]
	global_store_short v134, v33, s[4:5] offset:512
	s_add_u32 s4, s4, s56
	s_addc_u32 s5, s5, s3
	v_mov_b32_e32 v236, v16
	v_mov_b32_e32 v106, v124
	v_mov_b32_e32 v237, v16
	v_mov_b32_e32 v107, v124
	v_mov_b32_e32 v238, v16
	v_mov_b32_e32 v108, v124
	v_mov_b32_e32 v239, v16
	v_mov_b32_e32 v109, v124
	v_mov_b32_e32 v240, v16
	v_mov_b32_e32 v110, v124
	v_mov_b32_e32 v241, v16
	v_mov_b32_e32 v111, v124
	v_mov_b32_e32 v242, v16
	v_mov_b32_e32 v112, v124
	v_mov_b32_e32 v243, v16
	v_mov_b32_e32 v113, v124
	v_mov_b32_e32 v244, v16
	v_mov_b32_e32 v114, v124
	v_mov_b32_e32 v245, v16
	v_mov_b32_e32 v115, v124
	v_mov_b32_e32 v246, v16
	v_mov_b32_e32 v116, v124
	v_mov_b32_e32 v247, v16
	v_mov_b32_e32 v117, v124
	v_mov_b32_e32 v248, v16
	v_mov_b32_e32 v118, v124
	v_mov_b32_e32 v249, v16
	v_mov_b32_e32 v119, v124
	v_mov_b32_e32 v250, v16
	v_mov_b32_e32 v120, v124
	v_mov_b32_e32 v251, v16
	v_mov_b32_e32 v121, v124
	s_nop 1
	v_mfma_f32_32x32x16_bf16 v[236:251], v[4:7], v[8:11], v[236:251]
	v_mfma_f32_32x32x16_bf16 v[106:121], v[4:7], v[12:15], v[106:121]
	s_nop 15
	s_nop 15
	v_permlane32_swap_b32 v236, v106
	v_permlane32_swap_b32 v237, v107
	v_permlane32_swap_b32 v238, v108
	v_permlane32_swap_b32 v239, v109
	v_permlane32_swap_b32 v240, v110
	v_permlane32_swap_b32 v241, v111
	v_permlane32_swap_b32 v242, v112
	v_permlane32_swap_b32 v243, v113
	v_permlane32_swap_b32 v244, v114
	v_permlane32_swap_b32 v245, v115
	v_permlane32_swap_b32 v246, v116
	v_permlane32_swap_b32 v247, v117
	v_permlane32_swap_b32 v248, v118
	v_permlane32_swap_b32 v249, v119
	v_permlane32_swap_b32 v250, v120
	v_permlane32_swap_b32 v251, v121
	v_mul_f32_e64 v18, |v236|, s1
	v_mul_f32_e64 v19, |v237|, s1
	v_mul_f32_e64 v20, |v238|, s1
	v_mul_f32_e64 v21, |v239|, s1
	v_mul_f32_e64 v22, |v106|, s1
	v_mul_f32_e64 v23, |v107|, s1
	v_mul_f32_e64 v24, |v108|, s1
	v_mul_f32_e64 v25, |v109|, s1
	v_mul_f32_e64 v26, |v240|, s1
	v_mul_f32_e64 v27, |v241|, s1
	v_mul_f32_e64 v28, |v242|, s1
	v_mul_f32_e64 v29, |v243|, s1
	v_mul_f32_e64 v30, |v110|, s1
	v_mul_f32_e64 v31, |v111|, s1
	v_mul_f32_e64 v32, |v112|, s1
	v_mul_f32_e64 v33, |v113|, s1
	v_exp_f32_e32 v18, v18
	v_exp_f32_e32 v19, v19
	v_exp_f32_e32 v20, v20
	v_exp_f32_e32 v21, v21
	v_exp_f32_e32 v22, v22
	v_exp_f32_e32 v23, v23
	v_exp_f32_e32 v24, v24
	v_exp_f32_e32 v25, v25
	v_exp_f32_e32 v26, v26
	v_exp_f32_e32 v27, v27
	v_exp_f32_e32 v28, v28
	v_exp_f32_e32 v29, v29
	v_exp_f32_e32 v30, v30
	v_exp_f32_e32 v31, v31
	v_exp_f32_e32 v32, v32
	v_exp_f32_e32 v33, v33
	v_max_f32_e64 v236, -v236, 0
	v_max_f32_e64 v237, -v237, 0
	v_max_f32_e64 v238, -v238, 0
	v_max_f32_e64 v239, -v239, 0
	v_max_f32_e64 v106, -v106, 0
	v_max_f32_e64 v107, -v107, 0
	v_max_f32_e64 v108, -v108, 0
	v_max_f32_e64 v109, -v109, 0
	v_max_f32_e64 v240, -v240, 0
	v_max_f32_e64 v241, -v241, 0
	v_max_f32_e64 v242, -v242, 0
	v_max_f32_e64 v243, -v243, 0
	v_max_f32_e64 v110, -v110, 0
	v_max_f32_e64 v111, -v111, 0
	v_max_f32_e64 v112, -v112, 0
	v_max_f32_e64 v113, -v113, 0
	v_add_f32_e32 v18, 1.0, v18
	v_add_f32_e32 v19, 1.0, v19
	v_add_f32_e32 v20, 1.0, v20
	v_add_f32_e32 v21, 1.0, v21
	v_add_f32_e32 v22, 1.0, v22
	v_add_f32_e32 v23, 1.0, v23
	v_add_f32_e32 v24, 1.0, v24
	v_add_f32_e32 v25, 1.0, v25
	v_add_f32_e32 v26, 1.0, v26
	v_add_f32_e32 v27, 1.0, v27
	v_add_f32_e32 v28, 1.0, v28
	v_add_f32_e32 v29, 1.0, v29
	v_add_f32_e32 v30, 1.0, v30
	v_add_f32_e32 v31, 1.0, v31
	v_add_f32_e32 v32, 1.0, v32
	v_add_f32_e32 v33, 1.0, v33
	v_log_f32_e32 v18, v18
	v_log_f32_e32 v19, v19
	v_log_f32_e32 v20, v20
	v_log_f32_e32 v21, v21
	v_log_f32_e32 v22, v22
	v_log_f32_e32 v23, v23
	v_log_f32_e32 v24, v24
	v_log_f32_e32 v25, v25
	v_log_f32_e32 v26, v26
	v_log_f32_e32 v27, v27
	v_log_f32_e32 v28, v28
	v_log_f32_e32 v29, v29
	v_log_f32_e32 v30, v30
	v_log_f32_e32 v31, v31
	v_log_f32_e32 v32, v32
	v_log_f32_e32 v33, v33
	v_fmac_f32_e32 v236, 0x3f317218, v18
	v_fmac_f32_e32 v237, 0x3f317218, v19
	v_fmac_f32_e32 v238, 0x3f317218, v20
	v_fmac_f32_e32 v239, 0x3f317218, v21
	v_fmac_f32_e32 v106, 0x3f317218, v22
	v_fmac_f32_e32 v107, 0x3f317218, v23
	v_fmac_f32_e32 v108, 0x3f317218, v24
	v_fmac_f32_e32 v109, 0x3f317218, v25
	v_fmac_f32_e32 v240, 0x3f317218, v26
	v_fmac_f32_e32 v241, 0x3f317218, v27
	v_fmac_f32_e32 v242, 0x3f317218, v28
	v_fmac_f32_e32 v243, 0x3f317218, v29
	v_fmac_f32_e32 v110, 0x3f317218, v30
	v_fmac_f32_e32 v111, 0x3f317218, v31
	v_fmac_f32_e32 v112, 0x3f317218, v32
	v_fmac_f32_e32 v113, 0x3f317218, v33
	v_fma_f32 v70, v236, s49, v17
	v_fma_f32 v71, v237, s49, v70
	v_fma_f32 v72, v238, s49, v71
	v_fma_f32 v73, v239, s49, v72
	v_fma_f32 v74, v106, s49, v73
	v_fma_f32 v75, v107, s49, v74
	v_fma_f32 v76, v108, s49, v75
	v_fma_f32 v77, v109, s49, v76
	v_fma_f32 v78, v240, s49, v77
	v_fma_f32 v79, v241, s49, v78
	v_fma_f32 v80, v242, s49, v79
	v_fma_f32 v81, v243, s49, v80
	v_fma_f32 v82, v110, s49, v81
	v_fma_f32 v83, v111, s49, v82
	v_fma_f32 v84, v112, s49, v83
	v_fma_f32 v85, v113, s49, v84
	v_mov_b32_e32 v17, v85
	s_waitcnt vmcnt(32)
; __device__ __forceinline__ unsigned f2bf(float f) { unsigned r; asm("v_cvt_pk_bf16_f32 %0, %1, %1" : "=v"(r) : "v"(f)); return r & 0xffffu; }
; __device__ __forceinline__ void gl1_item(PREF p, int l, int item, bool valid, LAS unsigned char* pl, int sw, int lane) {
;     ...
;                 for (int ss = 0; ss < 16; ++ss) { const int s = (g4 + 1) * 16 + ss; const int i = d ? 63 - s : s; const bf16_t* pr = P + (size_t)(row0 + i * rstride) * PW + h * 64 + lane;
;                     qn[ss] = __builtin_bit_cast(float, (unsigned)pr[1024]); kn[ss] = __builtin_bit_cast(float, (unsigned)pr[1280]); }
;                 __builtin_amdgcn_sched_barrier(0);
;             }
;             float gv[16];
; #pragma unroll
;             for (int ss = 0; ss < 16; ++ss) { const int s = g4 * 16 + ss; const int i = d ? 63 - s : s;
;                 float z = bup;
; #pragma unroll
;                 for (int r2 = 0; r2 < 8; ++r2) { const unsigned w = (unsigned)__builtin_amdgcn_readlane((int)lrp[r2], i);
;                     z = __builtin_amdgcn_fdot2_f32_bf16(__builtin_bit_cast(bf16x2_t, w), __builtin_bit_cast(bf16x2_t, wupp[r2]), z, false); }
;                 gv[ss] = -(fmaxf(-z, 0.f) + __logf(1.f + __expf(-fabsf(z)))) * (1.f / 16.f);
;                 __builtin_amdgcn_sched_barrier(0);
;             }
; #pragma unroll
;             for (int ss = 0; ss < 16; ++ss) { const int s = g4 * 16 + ss; const int i = d ? 63 - s : s; const size_t rowi = (size_t)(row0 + i * rstride);
;                 bc += gv[ss];
;                 const float en = __expf(-bc), ep = __expf(bc);
;                 const float kt = kc[ss] * en, qt = qc[ss] * 0.125f * ep;
;                 const unsigned ktb = f2bf(kt);
;                 sKt[lane * 72 + i] = (bf16_t)ktb;
;                 QK[rowi * 1024 + d * 512 + h * 64 + lane] = (bf16_t)f2bf(qt);
;                 QK[rowi * 1024 + d * 512 + 256 + h * 64 + lane] = (bf16_t)ktb;
	global_load_short_d16_hi v180, v134, s[6:7]
	global_load_short_d16_hi v196, v134, s[6:7] offset:512
	s_add_u32 s6, s6, s54
	s_addc_u32 s7, s7, s55
	global_load_short_d16_hi v181, v134, s[6:7]
	global_load_short_d16_hi v197, v134, s[6:7] offset:512
	s_add_u32 s6, s6, s54
	s_addc_u32 s7, s7, s55
	global_load_short_d16_hi v182, v134, s[6:7]
	global_load_short_d16_hi v198, v134, s[6:7] offset:512
	s_add_u32 s6, s6, s54
	s_addc_u32 s7, s7, s55
	global_load_short_d16_hi v183, v134, s[6:7]
	global_load_short_d16_hi v199, v134, s[6:7] offset:512
	s_add_u32 s6, s6, s54
	s_addc_u32 s7, s7, s55
	global_load_short_d16_hi v184, v134, s[6:7]
	global_load_short_d16_hi v200, v134, s[6:7] offset:512
	s_add_u32 s6, s6, s54
	s_addc_u32 s7, s7, s55
	global_load_short_d16_hi v185, v134, s[6:7]
	global_load_short_d16_hi v201, v134, s[6:7] offset:512
	s_add_u32 s6, s6, s54
	s_addc_u32 s7, s7, s55
	global_load_short_d16_hi v186, v134, s[6:7]
	global_load_short_d16_hi v202, v134, s[6:7] offset:512
	s_add_u32 s6, s6, s54
	s_addc_u32 s7, s7, s55
	global_load_short_d16_hi v187, v134, s[6:7]
	global_load_short_d16_hi v203, v134, s[6:7] offset:512
	s_add_u32 s6, s6, s54
	s_addc_u32 s7, s7, s55
	global_load_short_d16_hi v188, v134, s[6:7]
	global_load_short_d16_hi v204, v134, s[6:7] offset:512
	s_add_u32 s6, s6, s54
	s_addc_u32 s7, s7, s55
	global_load_short_d16_hi v189, v134, s[6:7]
	global_load_short_d16_hi v205, v134, s[6:7] offset:512
	s_add_u32 s6, s6, s54
	s_addc_u32 s7, s7, s55
	global_load_short_d16_hi v190, v134, s[6:7]
	global_load_short_d16_hi v206, v134, s[6:7] offset:512
	s_add_u32 s6, s6, s54
	s_addc_u32 s7, s7, s55
	global_load_short_d16_hi v191, v134, s[6:7]
	global_load_short_d16_hi v207, v134, s[6:7] offset:512
	s_add_u32 s6, s6, s54
	s_addc_u32 s7, s7, s55
	global_load_short_d16_hi v192, v134, s[6:7]
	global_load_short_d16_hi v208, v134, s[6:7] offset:512
	s_add_u32 s6, s6, s54
	s_addc_u32 s7, s7, s55
	global_load_short_d16_hi v193, v134, s[6:7]
	global_load_short_d16_hi v209, v134, s[6:7] offset:512
	s_add_u32 s6, s6, s54
	s_addc_u32 s7, s7, s55
	global_load_short_d16_hi v194, v134, s[6:7]
	global_load_short_d16_hi v210, v134, s[6:7] offset:512
	s_add_u32 s6, s6, s54
	s_addc_u32 s7, s7, s55
	global_load_short_d16_hi v195, v134, s[6:7]
	global_load_short_d16_hi v211, v134, s[6:7] offset:512
	s_add_u32 s6, s6, s54
	s_addc_u32 s7, s7, s55
	v_mul_f32_e32 v18, 0xbfb8aa3b, v70
	v_mul_f32_e32 v19, 0xbfb8aa3b, v71
	v_mul_f32_e32 v20, 0xbfb8aa3b, v72
	v_mul_f32_e32 v21, 0xbfb8aa3b, v73
	v_mul_f32_e32 v22, 0xbfb8aa3b, v74
	v_mul_f32_e32 v23, 0xbfb8aa3b, v75
	v_mul_f32_e32 v24, 0xbfb8aa3b, v76
	v_mul_f32_e32 v25, 0xbfb8aa3b, v77
	v_mul_f32_e32 v26, 0xbfb8aa3b, v78
	v_mul_f32_e32 v27, 0xbfb8aa3b, v79
	v_mul_f32_e32 v28, 0xbfb8aa3b, v80
	v_mul_f32_e32 v29, 0xbfb8aa3b, v81
	v_mul_f32_e32 v30, 0xbfb8aa3b, v82
	v_mul_f32_e32 v31, 0xbfb8aa3b, v83
	v_mul_f32_e32 v32, 0xbfb8aa3b, v84
	v_mul_f32_e32 v33, 0xbfb8aa3b, v85
	v_exp_f32_e64 v236, -v18
	v_exp_f32_e64 v237, -v19
	v_exp_f32_e64 v238, -v20
	v_exp_f32_e64 v239, -v21
	v_exp_f32_e64 v106, -v22
	v_exp_f32_e64 v107, -v23
	v_exp_f32_e64 v108, -v24
	v_exp_f32_e64 v109, -v25
	v_exp_f32_e64 v240, -v26
	v_exp_f32_e64 v241, -v27
	v_exp_f32_e64 v242, -v28
	v_exp_f32_e64 v243, -v29
	v_exp_f32_e64 v110, -v30
	v_exp_f32_e64 v111, -v31
	v_exp_f32_e64 v112, -v32
	v_exp_f32_e64 v113, -v33
	v_exp_f32_e32 v18, v18
	v_exp_f32_e32 v19, v19
	v_exp_f32_e32 v20, v20
	v_exp_f32_e32 v21, v21
	v_exp_f32_e32 v22, v22
	v_exp_f32_e32 v23, v23
	v_exp_f32_e32 v24, v24
	v_exp_f32_e32 v25, v25
	v_exp_f32_e32 v26, v26
	v_exp_f32_e32 v27, v27
	v_exp_f32_e32 v28, v28
	v_exp_f32_e32 v29, v29
	v_exp_f32_e32 v30, v30
	v_exp_f32_e32 v31, v31
	v_exp_f32_e32 v32, v32
	v_exp_f32_e32 v33, v33
	v_mul_f32_e32 v18, v18, v164
	v_mul_f32_e32 v19, v19, v165
	v_mul_f32_e32 v20, v20, v166
	v_mul_f32_e32 v21, v21, v167
	v_mul_f32_e32 v22, v22, v168
	v_mul_f32_e32 v23, v23, v169
	v_mul_f32_e32 v24, v24, v170
	v_mul_f32_e32 v25, v25, v171
	v_mul_f32_e32 v26, v26, v172
	v_mul_f32_e32 v27, v27, v173
	v_mul_f32_e32 v28, v28, v174
	v_mul_f32_e32 v29, v29, v175
	v_mul_f32_e32 v30, v30, v176
	v_mul_f32_e32 v31, v31, v177
	v_mul_f32_e32 v32, v32, v178
	v_mul_f32_e32 v33, v33, v179
	v_mul_f32_e32 v70, 0x3e000000, v148
	v_mul_f32_e32 v71, 0x3e000000, v149
	v_mul_f32_e32 v72, 0x3e000000, v150
	v_mul_f32_e32 v73, 0x3e000000, v151
	v_mul_f32_e32 v74, 0x3e000000, v152
	v_mul_f32_e32 v75, 0x3e000000, v153
	v_mul_f32_e32 v76, 0x3e000000, v154
	v_mul_f32_e32 v77, 0x3e000000, v155
	v_mul_f32_e32 v78, 0x3e000000, v156
	v_mul_f32_e32 v79, 0x3e000000, v157
	v_mul_f32_e32 v80, 0x3e000000, v158
	v_mul_f32_e32 v81, 0x3e000000, v159
	v_mul_f32_e32 v82, 0x3e000000, v160
	v_mul_f32_e32 v83, 0x3e000000, v161
	v_mul_f32_e32 v84, 0x3e000000, v162
	v_mul_f32_e32 v85, 0x3e000000, v163
	v_mul_f32_e32 v236, v70, v236
	v_mul_f32_e32 v237, v71, v237
	v_mul_f32_e32 v238, v72, v238
	v_mul_f32_e32 v239, v73, v239
	v_mul_f32_e32 v106, v74, v106
	v_mul_f32_e32 v107, v75, v107
	v_mul_f32_e32 v108, v76, v108
	v_mul_f32_e32 v109, v77, v109
	v_mul_f32_e32 v240, v78, v240
	v_mul_f32_e32 v241, v79, v241
	v_mul_f32_e32 v242, v80, v242
	v_mul_f32_e32 v243, v81, v243
	v_mul_f32_e32 v110, v82, v110
	v_mul_f32_e32 v111, v83, v111
	v_mul_f32_e32 v112, v84, v112
	v_mul_f32_e32 v113, v85, v113
	v_cvt_pk_bf16_f32 v18, v18, v236
	v_cvt_pk_bf16_f32 v19, v19, v237
	v_cvt_pk_bf16_f32 v20, v20, v238
	v_cvt_pk_bf16_f32 v21, v21, v239
	v_cvt_pk_bf16_f32 v22, v22, v106
	v_cvt_pk_bf16_f32 v23, v23, v107
	v_cvt_pk_bf16_f32 v24, v24, v108
	v_cvt_pk_bf16_f32 v25, v25, v109
	v_cvt_pk_bf16_f32 v26, v26, v240
	v_cvt_pk_bf16_f32 v27, v27, v241
; __device__ __forceinline__ unsigned f2bf(float f) { unsigned r; asm("v_cvt_pk_bf16_f32 %0, %1, %1" : "=v"(r) : "v"(f)); return r & 0xffffu; }
; __device__ __forceinline__ void gl1_item(PREF p, int l, int item, bool valid, LAS unsigned char* pl, int sw, int lane) {
;     ...
;             for (int ss = 0; ss < 16; ++ss) { const int s = g4 * 16 + ss; const int i = d ? 63 - s : s;
;                 float z = bup;
; #pragma unroll
;                 for (int r2 = 0; r2 < 8; ++r2) { const unsigned w = (unsigned)__builtin_amdgcn_readlane((int)lrp[r2], i);
;                     z = __builtin_amdgcn_fdot2_f32_bf16(__builtin_bit_cast(bf16x2_t, w), __builtin_bit_cast(bf16x2_t, wupp[r2]), z, false); }
;                 gv[ss] = -(fmaxf(-z, 0.f) + __logf(1.f + __expf(-fabsf(z)))) * (1.f / 16.f);
;                 __builtin_amdgcn_sched_barrier(0);
;             }
;     ...
;             for (int ss = 0; ss < 16; ++ss) { const int s = g4 * 16 + ss; const int i = d ? 63 - s : s; const size_t rowi = (size_t)(row0 + i * rstride);
;                 bc += gv[ss];
;                 const float en = __expf(-bc), ep = __expf(bc);
;                 const float kt = kc[ss] * en, qt = qc[ss] * 0.125f * ep;
;                 const unsigned ktb = f2bf(kt);
;                 sKt[lane * 72 + i] = (bf16_t)ktb;
;                 QK[rowi * 1024 + d * 512 + h * 64 + lane] = (bf16_t)f2bf(qt);
;                 QK[rowi * 1024 + d * 512 + 256 + h * 64 + lane] = (bf16_t)ktb;
;             }
	v_cvt_pk_bf16_f32 v28, v28, v242
	v_cvt_pk_bf16_f32 v29, v29, v243
	v_cvt_pk_bf16_f32 v30, v30, v110
	v_cvt_pk_bf16_f32 v31, v31, v111
	v_cvt_pk_bf16_f32 v32, v32, v112
	v_cvt_pk_bf16_f32 v33, v33, v113
	ds_write_b16 v60, v18
	v_add_u32_e32 v60, v61, v60
	global_store_short_d16_hi v134, v18, s[4:5]
	global_store_short v134, v18, s[4:5] offset:512
	s_add_u32 s4, s4, s56
	s_addc_u32 s5, s5, s3
	ds_write_b16 v60, v19
	v_add_u32_e32 v60, v61, v60
	global_store_short_d16_hi v134, v19, s[4:5]
	global_store_short v134, v19, s[4:5] offset:512
	s_add_u32 s4, s4, s56
	s_addc_u32 s5, s5, s3
	ds_write_b16 v60, v20
	v_add_u32_e32 v60, v61, v60
	global_store_short_d16_hi v134, v20, s[4:5]
	global_store_short v134, v20, s[4:5] offset:512
	s_add_u32 s4, s4, s56
	s_addc_u32 s5, s5, s3
	ds_write_b16 v60, v21
	v_add_u32_e32 v60, v61, v60
	global_store_short_d16_hi v134, v21, s[4:5]
	global_store_short v134, v21, s[4:5] offset:512
	s_add_u32 s4, s4, s56
	s_addc_u32 s5, s5, s3
	ds_write_b16 v60, v22
	v_add_u32_e32 v60, v61, v60
	global_store_short_d16_hi v134, v22, s[4:5]
	global_store_short v134, v22, s[4:5] offset:512
	s_add_u32 s4, s4, s56
	s_addc_u32 s5, s5, s3
	ds_write_b16 v60, v23
	v_add_u32_e32 v60, v61, v60
	global_store_short_d16_hi v134, v23, s[4:5]
	global_store_short v134, v23, s[4:5] offset:512
	s_add_u32 s4, s4, s56
	s_addc_u32 s5, s5, s3
	ds_write_b16 v60, v24
	v_add_u32_e32 v60, v61, v60
	global_store_short_d16_hi v134, v24, s[4:5]
	global_store_short v134, v24, s[4:5] offset:512
	s_add_u32 s4, s4, s56
	s_addc_u32 s5, s5, s3
	ds_write_b16 v60, v25
	v_add_u32_e32 v60, v61, v60
	global_store_short_d16_hi v134, v25, s[4:5]
	global_store_short v134, v25, s[4:5] offset:512
	s_add_u32 s4, s4, s56
	s_addc_u32 s5, s5, s3
	ds_write_b16 v60, v26
	v_add_u32_e32 v60, v61, v60
	global_store_short_d16_hi v134, v26, s[4:5]
	global_store_short v134, v26, s[4:5] offset:512
	s_add_u32 s4, s4, s56
	s_addc_u32 s5, s5, s3
	ds_write_b16 v60, v27
	v_add_u32_e32 v60, v61, v60
	global_store_short_d16_hi v134, v27, s[4:5]
	global_store_short v134, v27, s[4:5] offset:512
	s_add_u32 s4, s4, s56
	s_addc_u32 s5, s5, s3
	ds_write_b16 v60, v28
	v_add_u32_e32 v60, v61, v60
	global_store_short_d16_hi v134, v28, s[4:5]
	global_store_short v134, v28, s[4:5] offset:512
	s_add_u32 s4, s4, s56
	s_addc_u32 s5, s5, s3
	ds_write_b16 v60, v29
	v_add_u32_e32 v60, v61, v60
	global_store_short_d16_hi v134, v29, s[4:5]
	global_store_short v134, v29, s[4:5] offset:512
	s_add_u32 s4, s4, s56
	s_addc_u32 s5, s5, s3
	ds_write_b16 v60, v30
	v_add_u32_e32 v60, v61, v60
	global_store_short_d16_hi v134, v30, s[4:5]
	global_store_short v134, v30, s[4:5] offset:512
	s_add_u32 s4, s4, s56
	s_addc_u32 s5, s5, s3
	ds_write_b16 v60, v31
	v_add_u32_e32 v60, v61, v60
	global_store_short_d16_hi v134, v31, s[4:5]
	global_store_short v134, v31, s[4:5] offset:512
	s_add_u32 s4, s4, s56
	s_addc_u32 s5, s5, s3
	ds_write_b16 v60, v32
	v_add_u32_e32 v60, v61, v60
	global_store_short_d16_hi v134, v32, s[4:5]
	global_store_short v134, v32, s[4:5] offset:512
	s_add_u32 s4, s4, s56
	s_addc_u32 s5, s5, s3
	ds_write_b16 v60, v33
	v_add_u32_e32 v60, v61, v60
	global_store_short_d16_hi v134, v33, s[4:5]
	global_store_short v134, v33, s[4:5] offset:512
	s_add_u32 s4, s4, s56
	s_addc_u32 s5, s5, s3
	v_mul_f32_e64 v18, |v244|, s1
	v_mul_f32_e64 v19, |v245|, s1
	v_mul_f32_e64 v20, |v246|, s1
	v_mul_f32_e64 v21, |v247|, s1
	v_mul_f32_e64 v22, |v114|, s1
	v_mul_f32_e64 v23, |v115|, s1
	v_mul_f32_e64 v24, |v116|, s1
	v_mul_f32_e64 v25, |v117|, s1
	v_mul_f32_e64 v26, |v248|, s1
	v_mul_f32_e64 v27, |v249|, s1
	v_mul_f32_e64 v28, |v250|, s1
	v_mul_f32_e64 v29, |v251|, s1
	v_mul_f32_e64 v30, |v118|, s1
	v_mul_f32_e64 v31, |v119|, s1
	v_mul_f32_e64 v32, |v120|, s1
	v_mul_f32_e64 v33, |v121|, s1
	v_exp_f32_e32 v18, v18
	v_exp_f32_e32 v19, v19
	v_exp_f32_e32 v20, v20
	v_exp_f32_e32 v21, v21
	v_exp_f32_e32 v22, v22
	v_exp_f32_e32 v23, v23
	v_exp_f32_e32 v24, v24
	v_exp_f32_e32 v25, v25
	v_exp_f32_e32 v26, v26
	v_exp_f32_e32 v27, v27
	v_exp_f32_e32 v28, v28
	v_exp_f32_e32 v29, v29
	v_exp_f32_e32 v30, v30
	v_exp_f32_e32 v31, v31
	v_exp_f32_e32 v32, v32
	v_exp_f32_e32 v33, v33
	v_max_f32_e64 v244, -v244, 0
	v_max_f32_e64 v245, -v245, 0
	v_max_f32_e64 v246, -v246, 0
	v_max_f32_e64 v247, -v247, 0
	v_max_f32_e64 v114, -v114, 0
	v_max_f32_e64 v115, -v115, 0
	v_max_f32_e64 v116, -v116, 0
	v_max_f32_e64 v117, -v117, 0
	v_max_f32_e64 v248, -v248, 0
	v_max_f32_e64 v249, -v249, 0
	v_max_f32_e64 v250, -v250, 0
	v_max_f32_e64 v251, -v251, 0
	v_max_f32_e64 v118, -v118, 0
	v_max_f32_e64 v119, -v119, 0
	v_max_f32_e64 v120, -v120, 0
	v_max_f32_e64 v121, -v121, 0
	v_add_f32_e32 v18, 1.0, v18
	v_add_f32_e32 v19, 1.0, v19
	v_add_f32_e32 v20, 1.0, v20
	v_add_f32_e32 v21, 1.0, v21
	v_add_f32_e32 v22, 1.0, v22
	v_add_f32_e32 v23, 1.0, v23
	v_add_f32_e32 v24, 1.0, v24
	v_add_f32_e32 v25, 1.0, v25
	v_add_f32_e32 v26, 1.0, v26
	v_add_f32_e32 v27, 1.0, v27
	v_add_f32_e32 v28, 1.0, v28
	v_add_f32_e32 v29, 1.0, v29
	v_add_f32_e32 v30, 1.0, v30
	v_add_f32_e32 v31, 1.0, v31
	v_add_f32_e32 v32, 1.0, v32
	v_add_f32_e32 v33, 1.0, v33
	v_log_f32_e32 v18, v18
	v_log_f32_e32 v19, v19
	v_log_f32_e32 v20, v20
	v_log_f32_e32 v21, v21
	v_log_f32_e32 v22, v22
	v_log_f32_e32 v23, v23
	v_log_f32_e32 v24, v24
	v_log_f32_e32 v25, v25
	v_log_f32_e32 v26, v26
	v_log_f32_e32 v27, v27
	v_log_f32_e32 v28, v28
	v_log_f32_e32 v29, v29
	v_log_f32_e32 v30, v30
	v_log_f32_e32 v31, v31
	v_log_f32_e32 v32, v32
	v_log_f32_e32 v33, v33
	v_fmac_f32_e32 v244, 0x3f317218, v18
	v_fmac_f32_e32 v245, 0x3f317218, v19
	v_fmac_f32_e32 v246, 0x3f317218, v20
	v_fmac_f32_e32 v247, 0x3f317218, v21
	v_fmac_f32_e32 v114, 0x3f317218, v22
	v_fmac_f32_e32 v115, 0x3f317218, v23
	v_fmac_f32_e32 v116, 0x3f317218, v24
	v_fmac_f32_e32 v117, 0x3f317218, v25
	v_fmac_f32_e32 v248, 0x3f317218, v26
	v_fmac_f32_e32 v249, 0x3f317218, v27
	v_fmac_f32_e32 v250, 0x3f317218, v28
	v_fmac_f32_e32 v251, 0x3f317218, v29
	v_fmac_f32_e32 v118, 0x3f317218, v30
	v_fmac_f32_e32 v119, 0x3f317218, v31
	v_fmac_f32_e32 v120, 0x3f317218, v32
	v_fmac_f32_e32 v121, 0x3f317218, v33
	v_fma_f32 v70, v244, s49, v17
	v_fma_f32 v71, v245, s49, v70
	v_fma_f32 v72, v246, s49, v71
	v_fma_f32 v73, v247, s49, v72
	v_fma_f32 v74, v114, s49, v73
	v_fma_f32 v75, v115, s49, v74
	v_fma_f32 v76, v116, s49, v75
	v_fma_f32 v77, v117, s49, v76
	v_fma_f32 v78, v248, s49, v77
	v_fma_f32 v79, v249, s49, v78
	v_fma_f32 v80, v250, s49, v79
	v_fma_f32 v81, v251, s49, v80
	v_fma_f32 v82, v118, s49, v81
	v_fma_f32 v83, v119, s49, v82
	v_fma_f32 v84, v120, s49, v83
	v_fma_f32 v85, v121, s49, v84
	v_mov_b32_e32 v17, v85
	s_waitcnt vmcnt(32)
; __device__ __forceinline__ unsigned f2bf(float f) { unsigned r; asm("v_cvt_pk_bf16_f32 %0, %1, %1" : "=v"(r) : "v"(f)); return r & 0xffffu; }
; __device__ __forceinline__ void gl1_item(PREF p, int l, int item, bool valid, LAS unsigned char* pl, int sw, int lane) {
;     ...
;             for (int ss = 0; ss < 16; ++ss) { const int s = g4 * 16 + ss; const int i = d ? 63 - s : s; const size_t rowi = (size_t)(row0 + i * rstride);
;                 bc += gv[ss];
;                 const float en = __expf(-bc), ep = __expf(bc);
;                 const float kt = kc[ss] * en, qt = qc[ss] * 0.125f * ep;
;                 const unsigned ktb = f2bf(kt);
;                 sKt[lane * 72 + i] = (bf16_t)ktb;
;                 QK[rowi * 1024 + d * 512 + h * 64 + lane] = (bf16_t)f2bf(qt);
;                 QK[rowi * 1024 + d * 512 + 256 + h * 64 + lane] = (bf16_t)ktb;
	v_mul_f32_e32 v18, 0xbfb8aa3b, v70
	v_mul_f32_e32 v19, 0xbfb8aa3b, v71
	v_mul_f32_e32 v20, 0xbfb8aa3b, v72
	v_mul_f32_e32 v21, 0xbfb8aa3b, v73
	v_mul_f32_e32 v22, 0xbfb8aa3b, v74
	v_mul_f32_e32 v23, 0xbfb8aa3b, v75
	v_mul_f32_e32 v24, 0xbfb8aa3b, v76
	v_mul_f32_e32 v25, 0xbfb8aa3b, v77
	v_mul_f32_e32 v26, 0xbfb8aa3b, v78
	v_mul_f32_e32 v27, 0xbfb8aa3b, v79
	v_mul_f32_e32 v28, 0xbfb8aa3b, v80
	v_mul_f32_e32 v29, 0xbfb8aa3b, v81
	v_mul_f32_e32 v30, 0xbfb8aa3b, v82
	v_mul_f32_e32 v31, 0xbfb8aa3b, v83
	v_mul_f32_e32 v32, 0xbfb8aa3b, v84
	v_mul_f32_e32 v33, 0xbfb8aa3b, v85
	v_exp_f32_e64 v244, -v18
	v_exp_f32_e64 v245, -v19
	v_exp_f32_e64 v246, -v20
	v_exp_f32_e64 v247, -v21
	v_exp_f32_e64 v114, -v22
	v_exp_f32_e64 v115, -v23
	v_exp_f32_e64 v116, -v24
	v_exp_f32_e64 v117, -v25
	v_exp_f32_e64 v248, -v26
	v_exp_f32_e64 v249, -v27
	v_exp_f32_e64 v250, -v28
	v_exp_f32_e64 v251, -v29
	v_exp_f32_e64 v118, -v30
	v_exp_f32_e64 v119, -v31
	v_exp_f32_e64 v120, -v32
	v_exp_f32_e64 v121, -v33
	v_exp_f32_e32 v18, v18
	v_exp_f32_e32 v19, v19
	v_exp_f32_e32 v20, v20
	v_exp_f32_e32 v21, v21
	v_exp_f32_e32 v22, v22
	v_exp_f32_e32 v23, v23
	v_exp_f32_e32 v24, v24
	v_exp_f32_e32 v25, v25
	v_exp_f32_e32 v26, v26
	v_exp_f32_e32 v27, v27
	v_exp_f32_e32 v28, v28
	v_exp_f32_e32 v29, v29
	v_exp_f32_e32 v30, v30
	v_exp_f32_e32 v31, v31
	v_exp_f32_e32 v32, v32
	v_exp_f32_e32 v33, v33
	v_mul_f32_e32 v18, v18, v196
	v_mul_f32_e32 v19, v19, v197
	v_mul_f32_e32 v20, v20, v198
	v_mul_f32_e32 v21, v21, v199
	v_mul_f32_e32 v22, v22, v200
	v_mul_f32_e32 v23, v23, v201
	v_mul_f32_e32 v24, v24, v202
	v_mul_f32_e32 v25, v25, v203
	v_mul_f32_e32 v26, v26, v204
	v_mul_f32_e32 v27, v27, v205
	v_mul_f32_e32 v28, v28, v206
	v_mul_f32_e32 v29, v29, v207
	v_mul_f32_e32 v30, v30, v208
	v_mul_f32_e32 v31, v31, v209
	v_mul_f32_e32 v32, v32, v210
	v_mul_f32_e32 v33, v33, v211
	v_mul_f32_e32 v70, 0x3e000000, v180
	v_mul_f32_e32 v71, 0x3e000000, v181
	v_mul_f32_e32 v72, 0x3e000000, v182
	v_mul_f32_e32 v73, 0x3e000000, v183
	v_mul_f32_e32 v74, 0x3e000000, v184
	v_mul_f32_e32 v75, 0x3e000000, v185
	v_mul_f32_e32 v76, 0x3e000000, v186
	v_mul_f32_e32 v77, 0x3e000000, v187
	v_mul_f32_e32 v78, 0x3e000000, v188
	v_mul_f32_e32 v79, 0x3e000000, v189
	v_mul_f32_e32 v80, 0x3e000000, v190
	v_mul_f32_e32 v81, 0x3e000000, v191
	v_mul_f32_e32 v82, 0x3e000000, v192
	v_mul_f32_e32 v83, 0x3e000000, v193
	v_mul_f32_e32 v84, 0x3e000000, v194
	v_mul_f32_e32 v85, 0x3e000000, v195
	v_mul_f32_e32 v244, v70, v244
	v_mul_f32_e32 v245, v71, v245
	v_mul_f32_e32 v246, v72, v246
	v_mul_f32_e32 v247, v73, v247
	v_mul_f32_e32 v114, v74, v114
	v_mul_f32_e32 v115, v75, v115
	v_mul_f32_e32 v116, v76, v116
	v_mul_f32_e32 v117, v77, v117
	v_mul_f32_e32 v248, v78, v248
	v_mul_f32_e32 v249, v79, v249
	v_mul_f32_e32 v250, v80, v250
	v_mul_f32_e32 v251, v81, v251
	v_mul_f32_e32 v118, v82, v118
	v_mul_f32_e32 v119, v83, v119
	v_mul_f32_e32 v120, v84, v120
	v_mul_f32_e32 v121, v85, v121
	v_cvt_pk_bf16_f32 v18, v18, v244
	v_cvt_pk_bf16_f32 v19, v19, v245
	v_cvt_pk_bf16_f32 v20, v20, v246
	v_cvt_pk_bf16_f32 v21, v21, v247
	v_cvt_pk_bf16_f32 v22, v22, v114
	v_cvt_pk_bf16_f32 v23, v23, v115
	v_cvt_pk_bf16_f32 v24, v24, v116
	v_cvt_pk_bf16_f32 v25, v25, v117
	v_cvt_pk_bf16_f32 v26, v26, v248
	v_cvt_pk_bf16_f32 v27, v27, v249
	v_cvt_pk_bf16_f32 v28, v28, v250
	v_cvt_pk_bf16_f32 v29, v29, v251
	v_cvt_pk_bf16_f32 v30, v30, v118
	v_cvt_pk_bf16_f32 v31, v31, v119
	v_cvt_pk_bf16_f32 v32, v32, v120
	v_cvt_pk_bf16_f32 v33, v33, v121
	ds_write_b16 v60, v18
	v_add_u32_e32 v60, v61, v60
	global_store_short_d16_hi v134, v18, s[4:5]
; __device__ __forceinline__ unsigned f2bf(float f) { unsigned r; asm("v_cvt_pk_bf16_f32 %0, %1, %1" : "=v"(r) : "v"(f)); return r & 0xffffu; }
; __device__ __forceinline__ void gl1_item(PREF p, int l, int item, bool valid, LAS unsigned char* pl, int sw, int lane) {
;     ...
;             for (int ss = 0; ss < 16; ++ss) { const int s = g4 * 16 + ss; const int i = d ? 63 - s : s; const size_t rowi = (size_t)(row0 + i * rstride);
;                 bc += gv[ss];
;                 const float en = __expf(-bc), ep = __expf(bc);
;                 const float kt = kc[ss] * en, qt = qc[ss] * 0.125f * ep;
;                 const unsigned ktb = f2bf(kt);
;                 sKt[lane * 72 + i] = (bf16_t)ktb;
;                 QK[rowi * 1024 + d * 512 + h * 64 + lane] = (bf16_t)f2bf(qt);
;                 QK[rowi * 1024 + d * 512 + 256 + h * 64 + lane] = (bf16_t)ktb;
;             }
; #pragma unroll
;             for (int ss = 0; ss < 16; ++ss) { qc[ss] = bf2f(__builtin_bit_cast(unsigned, qn[ss])); kc[ss] = bf2f(__builtin_bit_cast(unsigned, kn[ss])); }
;         }
;         const float Dv = __expf(bc);
;         sD[lane] = Dv; GLD[(size_t)(seq * NCH + cj) * 64 + lane] = Dv;
	global_store_short v134, v18, s[4:5] offset:512
	s_add_u32 s4, s4, s56
	s_addc_u32 s5, s5, s3
	ds_write_b16 v60, v19
	v_add_u32_e32 v60, v61, v60
	global_store_short_d16_hi v134, v19, s[4:5]
	global_store_short v134, v19, s[4:5] offset:512
	s_add_u32 s4, s4, s56
	s_addc_u32 s5, s5, s3
	ds_write_b16 v60, v20
	v_add_u32_e32 v60, v61, v60
	global_store_short_d16_hi v134, v20, s[4:5]
	global_store_short v134, v20, s[4:5] offset:512
	s_add_u32 s4, s4, s56
	s_addc_u32 s5, s5, s3
	ds_write_b16 v60, v21
	v_add_u32_e32 v60, v61, v60
	global_store_short_d16_hi v134, v21, s[4:5]
	global_store_short v134, v21, s[4:5] offset:512
	s_add_u32 s4, s4, s56
	s_addc_u32 s5, s5, s3
	ds_write_b16 v60, v22
	v_add_u32_e32 v60, v61, v60
	global_store_short_d16_hi v134, v22, s[4:5]
	global_store_short v134, v22, s[4:5] offset:512
	s_add_u32 s4, s4, s56
	s_addc_u32 s5, s5, s3
	ds_write_b16 v60, v23
	v_add_u32_e32 v60, v61, v60
	global_store_short_d16_hi v134, v23, s[4:5]
	global_store_short v134, v23, s[4:5] offset:512
	s_add_u32 s4, s4, s56
	s_addc_u32 s5, s5, s3
	ds_write_b16 v60, v24
	v_add_u32_e32 v60, v61, v60
	global_store_short_d16_hi v134, v24, s[4:5]
	global_store_short v134, v24, s[4:5] offset:512
	s_add_u32 s4, s4, s56
	s_addc_u32 s5, s5, s3
	ds_write_b16 v60, v25
	v_add_u32_e32 v60, v61, v60
	global_store_short_d16_hi v134, v25, s[4:5]
	global_store_short v134, v25, s[4:5] offset:512
	s_add_u32 s4, s4, s56
	s_addc_u32 s5, s5, s3
	ds_write_b16 v60, v26
	v_add_u32_e32 v60, v61, v60
	global_store_short_d16_hi v134, v26, s[4:5]
	global_store_short v134, v26, s[4:5] offset:512
	s_add_u32 s4, s4, s56
	s_addc_u32 s5, s5, s3
	ds_write_b16 v60, v27
	v_add_u32_e32 v60, v61, v60
	global_store_short_d16_hi v134, v27, s[4:5]
	global_store_short v134, v27, s[4:5] offset:512
	s_add_u32 s4, s4, s56
	s_addc_u32 s5, s5, s3
	ds_write_b16 v60, v28
	v_add_u32_e32 v60, v61, v60
	global_store_short_d16_hi v134, v28, s[4:5]
	global_store_short v134, v28, s[4:5] offset:512
	s_add_u32 s4, s4, s56
	s_addc_u32 s5, s5, s3
	ds_write_b16 v60, v29
	v_add_u32_e32 v60, v61, v60
	global_store_short_d16_hi v134, v29, s[4:5]
	global_store_short v134, v29, s[4:5] offset:512
	s_add_u32 s4, s4, s56
	s_addc_u32 s5, s5, s3
	ds_write_b16 v60, v30
	v_add_u32_e32 v60, v61, v60
	global_store_short_d16_hi v134, v30, s[4:5]
	global_store_short v134, v30, s[4:5] offset:512
	s_add_u32 s4, s4, s56
	s_addc_u32 s5, s5, s3
	ds_write_b16 v60, v31
	v_add_u32_e32 v60, v61, v60
	global_store_short_d16_hi v134, v31, s[4:5]
	global_store_short v134, v31, s[4:5] offset:512
	s_add_u32 s4, s4, s56
	s_addc_u32 s5, s5, s3
	ds_write_b16 v60, v32
	v_add_u32_e32 v60, v61, v60
	global_store_short_d16_hi v134, v32, s[4:5]
	global_store_short v134, v32, s[4:5] offset:512
	s_add_u32 s4, s4, s56
	s_addc_u32 s5, s5, s3
	ds_write_b16 v60, v33
	v_add_u32_e32 v60, v61, v60
	global_store_short_d16_hi v134, v33, s[4:5]
	global_store_short v134, v33, s[4:5] offset:512
	s_add_u32 s4, s4, s56
	s_addc_u32 s5, s5, s3
	v_mul_f32_e32 v18, 0x3fb8aa3b, v17
	v_exp_f32_e32 v18, v18
	v_readlane_b32 s50, v253, 55
	v_readlane_b32 s51, v253, 56
	v_readlane_b32 s45, v254, 11
	s_nop 3
	s_load_dwordx2 s[46:47], s[50:51], 0xc0
	s_and_b32 s48, s38, 1
	s_lshr_b32 s45, s45, 7
	s_mul_i32 s45, s45, 0x9200
	s_lshl_b32 s48, s48, 8
	s_add_i32 s45, s45, s48
	v_lshl_add_u32 v86, v64, 2, s45
	ds_write_b32 v86, v18 offset:36864
	s_or_b32 s45, s42, s38
	s_mulk_i32 s45, 0x104
	s_add_i32 s45, s45, s41
	s_lshl_b32 s45, s45, 8
	s_waitcnt lgkmcnt(0)
	s_add_u32 s46, s46, 0xd00000
	s_addc_u32 s47, s47, 0
	s_add_u32 s46, s46, s45
	s_addc_u32 s47, s47, 0
	global_store_dword v135, v18, s[46:47]
